# P0 weight-transpose loops unrolled x2: both 16-load batches issued before the first LDS write (32 loads in flight per wave); plus 3-deep conv on GLU-idle workgroups, R1/R3 epilogue dwordx4 pairing, S5
# baseline (speedup 1.0000x reference)
.LBB0_26:
	s_lshl_b32 s52, s12, 1
	s_lshl_b32 s53, s13, 1
	v_or_b32_e32 v6, s53, v16
	s_add_i32 s60, s52, 4
	s_add_i32 s61, s53, 4
	v_mov_b32_e32 v29, v7
	s_add_i32 s63, s53, 8
	v_lshlrev_b64 v[42:43], 12, v[6:7]
	v_or_b32_e32 v28, s60, v3
	v_or_b32_e32 v6, s61, v16
	v_mov_b32_e32 v25, v7
	v_or_b32_e32 v24, s52, v3
	s_add_i32 s65, s53, 12
	v_lshlrev_b64 v[28:29], 12, v[28:29]
	v_lshlrev_b64 v[44:45], 12, v[6:7]
	v_or_b32_e32 v6, s63, v16
	s_add_i32 s62, s52, 8
	s_add_i32 s64, s52, 12
	s_add_i32 s67, s53, 16
	v_lshlrev_b64 v[24:25], 12, v[24:25]
	v_lshl_add_u64 v[42:43], v[14:15], 0, v[42:43]
	v_lshl_add_u64 v[28:29], v[14:15], 0, v[28:29]
	v_lshlrev_b64 v[46:47], 12, v[6:7]
	v_or_b32_e32 v6, s65, v16
	v_mov_b32_e32 v31, v7
	v_mov_b32_e32 v33, v7
	s_add_i32 s69, s53, 20
	v_or_b32_e32 v30, s62, v3
	v_or_b32_e32 v32, s64, v3
	v_lshl_add_u64 v[24:25], v[14:15], 0, v[24:25]
	v_lshl_add_u64 v[44:45], v[14:15], 0, v[44:45]
	global_load_dword v11, v[42:43], off
	global_load_dword v13, v[24:25], off
	global_load_dword v58, v[44:45], off
	global_load_dword v59, v[28:29], off
	v_lshlrev_b64 v[28:29], 12, v[6:7]
	v_or_b32_e32 v6, s67, v16
	s_add_i32 s66, s52, 16
	s_add_i32 s68, s52, 20
	s_add_i32 s71, s53, 24
	v_lshlrev_b64 v[30:31], 12, v[30:31]
	v_lshlrev_b64 v[32:33], 12, v[32:33]
	v_lshl_add_u64 v[24:25], v[14:15], 0, v[46:47]
	v_lshl_add_u64 v[28:29], v[14:15], 0, v[28:29]
	v_lshlrev_b64 v[42:43], 12, v[6:7]
	v_or_b32_e32 v6, s69, v16
	v_mov_b32_e32 v35, v7
	v_mov_b32_e32 v37, v7
	s_add_i32 s70, s52, 24
	s_add_i32 s72, s52, 28
	s_add_i32 s73, s53, 28
	v_or_b32_e32 v34, s66, v3
	v_or_b32_e32 v36, s68, v3
	v_lshl_add_u64 v[30:31], v[14:15], 0, v[30:31]
	v_lshl_add_u64 v[32:33], v[14:15], 0, v[32:33]
	global_load_dword v60, v[24:25], off
	global_load_dword v61, v[30:31], off
	global_load_dword v62, v[28:29], off
	global_load_dword v63, v[32:33], off
	v_lshlrev_b64 v[28:29], 12, v[6:7]
	v_or_b32_e32 v6, s71, v16
	v_mov_b32_e32 v39, v7
	v_mov_b32_e32 v41, v7
	v_or_b32_e32 v38, s70, v3
	v_or_b32_e32 v40, s72, v3
	v_lshlrev_b64 v[34:35], 12, v[34:35]
	v_lshlrev_b64 v[36:37], 12, v[36:37]
	v_lshl_add_u64 v[24:25], v[14:15], 0, v[42:43]
	v_lshl_add_u64 v[28:29], v[14:15], 0, v[28:29]
	v_lshlrev_b64 v[30:31], 12, v[6:7]
	v_or_b32_e32 v6, s73, v16
	v_lshlrev_b64 v[38:39], 12, v[38:39]
	v_lshlrev_b64 v[40:41], 12, v[40:41]
	v_lshl_add_u64 v[34:35], v[14:15], 0, v[34:35]
	v_lshl_add_u64 v[36:37], v[14:15], 0, v[36:37]
	global_load_dword v64, v[24:25], off
	global_load_dword v65, v[34:35], off
	global_load_dword v66, v[28:29], off
	global_load_dword v67, v[36:37], off
	v_lshl_add_u64 v[24:25], v[14:15], 0, v[30:31]
	v_lshlrev_b64 v[28:29], 12, v[6:7]
	v_lshl_add_u64 v[38:39], v[14:15], 0, v[38:39]
	v_lshl_add_u64 v[40:41], v[14:15], 0, v[40:41]
	v_lshl_add_u64 v[28:29], v[14:15], 0, v[28:29]
	global_load_dword v6, v[24:25], off
	global_load_dword v68, v[38:39], off
	global_load_dword v69, v[28:29], off
	global_load_dword v70, v[40:41], off
	v_or_b32_e32 v28, s52, v1
	v_or_b32_e32 v24, s53, v2
	s_add_i32 s13, s13, 16
	s_add_i32 s12, s12, 16
	s_add_i32 s51, s51, -16
	v_mad_u64_u32 v[24:25], s[52:53], v24, s16, v[8:9]
	v_mad_u64_u32 v[28:29], s[52:53], v28, s16, v[8:9]
	v_or_b32_e32 v25, s60, v1
	v_or_b32_e32 v29, s61, v2
	v_or_b32_e32 v36, s62, v1
	v_or_b32_e32 v34, s63, v2
	v_or_b32_e32 v40, s64, v1
	v_or_b32_e32 v38, s65, v2
	v_or_b32_e32 v44, s66, v1
	v_or_b32_e32 v42, s67, v2
	v_or_b32_e32 v48, s68, v1
	v_or_b32_e32 v46, s69, v2
	v_or_b32_e32 v52, s70, v1
	v_or_b32_e32 v50, s71, v2
	v_or_b32_e32 v56, s72, v1
	v_or_b32_e32 v54, s73, v2
	v_mad_u64_u32 v[30:31], s[52:53], v29, s16, v[8:9]
	v_mad_u64_u32 v[32:33], s[52:53], v25, s16, v[8:9]
	v_mad_u64_u32 v[34:35], s[52:53], v34, s16, v[8:9]
	v_mad_u64_u32 v[36:37], s[52:53], v36, s16, v[8:9]
	v_mad_u64_u32 v[38:39], s[52:53], v38, s16, v[8:9]
	v_mad_u64_u32 v[40:41], s[52:53], v40, s16, v[8:9]
	v_mad_u64_u32 v[42:43], s[52:53], v42, s16, v[8:9]
	v_mad_u64_u32 v[44:45], s[52:53], v44, s16, v[8:9]
	v_mad_u64_u32 v[46:47], s[52:53], v46, s16, v[8:9]
	v_mad_u64_u32 v[48:49], s[52:53], v48, s16, v[8:9]
	v_mad_u64_u32 v[50:51], s[52:53], v50, s16, v[8:9]
	v_mad_u64_u32 v[52:53], s[52:53], v52, s16, v[8:9]
	v_mad_u64_u32 v[54:55], s[52:53], v54, s16, v[8:9]
	v_mad_u64_u32 v[56:57], s[52:53], v56, s16, v[8:9]
	v_mov_b32_e32 v147, v1
	v_mov_b32_e32 v148, v2
	v_mov_b32_e32 v149, v3
	v_mov_b32_e32 v153, v7
	v_mov_b32_e32 v154, v8
	v_mov_b32_e32 v155, v9
	v_mov_b32_e32 v160, v14
	v_mov_b32_e32 v161, v15
	v_mov_b32_e32 v162, v16
	s_lshl_b32 s52, s12, 1
	s_lshl_b32 s53, s13, 1
	v_or_b32_e32 v152, s53, v162
	s_add_i32 s60, s52, 4
	s_add_i32 s61, s53, 4
	v_mov_b32_e32 v175, v153
	s_add_i32 s63, s53, 8
	v_lshlrev_b64 v[188:189], 12, v[152:153]
	v_or_b32_e32 v174, s60, v149
	v_or_b32_e32 v152, s61, v162
	v_mov_b32_e32 v171, v153
	v_or_b32_e32 v170, s52, v149
	s_add_i32 s65, s53, 12
	v_lshlrev_b64 v[174:175], 12, v[174:175]
	v_lshlrev_b64 v[190:191], 12, v[152:153]
	v_or_b32_e32 v152, s63, v162
	s_add_i32 s62, s52, 8
	s_add_i32 s64, s52, 12
	s_add_i32 s67, s53, 16
	v_lshlrev_b64 v[170:171], 12, v[170:171]
	v_lshl_add_u64 v[188:189], v[160:161], 0, v[188:189]
	v_lshl_add_u64 v[174:175], v[160:161], 0, v[174:175]
	v_lshlrev_b64 v[192:193], 12, v[152:153]
	v_or_b32_e32 v152, s65, v162
	v_mov_b32_e32 v177, v153
	v_mov_b32_e32 v179, v153
	s_add_i32 s69, s53, 20
	v_or_b32_e32 v176, s62, v149
	v_or_b32_e32 v178, s64, v149
	v_lshl_add_u64 v[170:171], v[160:161], 0, v[170:171]
	v_lshl_add_u64 v[190:191], v[160:161], 0, v[190:191]
	global_load_dword v157, v[188:189], off
	global_load_dword v159, v[170:171], off
	global_load_dword v204, v[190:191], off
	global_load_dword v205, v[174:175], off
	v_lshlrev_b64 v[174:175], 12, v[152:153]
	v_or_b32_e32 v152, s67, v162
	s_add_i32 s66, s52, 16
	s_add_i32 s68, s52, 20
	s_add_i32 s71, s53, 24
	v_lshlrev_b64 v[176:177], 12, v[176:177]
	v_lshlrev_b64 v[178:179], 12, v[178:179]
	v_lshl_add_u64 v[170:171], v[160:161], 0, v[192:193]
	v_lshl_add_u64 v[174:175], v[160:161], 0, v[174:175]
	v_lshlrev_b64 v[188:189], 12, v[152:153]
	v_or_b32_e32 v152, s69, v162
	v_mov_b32_e32 v181, v153
	v_mov_b32_e32 v183, v153
	s_add_i32 s70, s52, 24
	s_add_i32 s72, s52, 28
	s_add_i32 s73, s53, 28
	v_or_b32_e32 v180, s66, v149
	v_or_b32_e32 v182, s68, v149
	v_lshl_add_u64 v[176:177], v[160:161], 0, v[176:177]
	v_lshl_add_u64 v[178:179], v[160:161], 0, v[178:179]
	global_load_dword v206, v[170:171], off
	global_load_dword v207, v[176:177], off
	global_load_dword v208, v[174:175], off
	global_load_dword v209, v[178:179], off
	v_lshlrev_b64 v[174:175], 12, v[152:153]
	v_or_b32_e32 v152, s71, v162
	v_mov_b32_e32 v185, v153
	v_mov_b32_e32 v187, v153
	v_or_b32_e32 v184, s70, v149
	v_or_b32_e32 v186, s72, v149
	v_lshlrev_b64 v[180:181], 12, v[180:181]
	v_lshlrev_b64 v[182:183], 12, v[182:183]
	v_lshl_add_u64 v[170:171], v[160:161], 0, v[188:189]
	v_lshl_add_u64 v[174:175], v[160:161], 0, v[174:175]
	v_lshlrev_b64 v[176:177], 12, v[152:153]
	v_or_b32_e32 v152, s73, v162
	v_lshlrev_b64 v[184:185], 12, v[184:185]
	v_lshlrev_b64 v[186:187], 12, v[186:187]
	v_lshl_add_u64 v[180:181], v[160:161], 0, v[180:181]
	v_lshl_add_u64 v[182:183], v[160:161], 0, v[182:183]
	global_load_dword v210, v[170:171], off
	global_load_dword v211, v[180:181], off
	global_load_dword v212, v[174:175], off
	global_load_dword v213, v[182:183], off
	v_lshl_add_u64 v[170:171], v[160:161], 0, v[176:177]
	v_lshlrev_b64 v[174:175], 12, v[152:153]
	v_lshl_add_u64 v[184:185], v[160:161], 0, v[184:185]
	v_lshl_add_u64 v[186:187], v[160:161], 0, v[186:187]
	v_lshl_add_u64 v[174:175], v[160:161], 0, v[174:175]
	global_load_dword v152, v[170:171], off
	global_load_dword v214, v[184:185], off
	global_load_dword v215, v[174:175], off
	global_load_dword v216, v[186:187], off
	v_or_b32_e32 v174, s52, v147
	v_or_b32_e32 v170, s53, v148
	s_add_i32 s13, s13, 16
	s_add_i32 s12, s12, 16
	s_add_i32 s51, s51, -16
	v_mad_u64_u32 v[170:171], s[52:53], v170, s16, v[154:155]
	v_mad_u64_u32 v[174:175], s[52:53], v174, s16, v[154:155]
	v_or_b32_e32 v171, s60, v147
	v_or_b32_e32 v175, s61, v148
	v_or_b32_e32 v182, s62, v147
	v_or_b32_e32 v180, s63, v148
	v_or_b32_e32 v186, s64, v147
	v_or_b32_e32 v184, s65, v148
	v_or_b32_e32 v190, s66, v147
	v_or_b32_e32 v188, s67, v148
	v_or_b32_e32 v194, s68, v147
	v_or_b32_e32 v192, s69, v148
	v_or_b32_e32 v198, s70, v147
	v_or_b32_e32 v196, s71, v148
	v_or_b32_e32 v202, s72, v147
	v_or_b32_e32 v200, s73, v148
	v_mad_u64_u32 v[176:177], s[52:53], v175, s16, v[154:155]
	v_mad_u64_u32 v[178:179], s[52:53], v171, s16, v[154:155]
	v_mad_u64_u32 v[180:181], s[52:53], v180, s16, v[154:155]
	v_mad_u64_u32 v[182:183], s[52:53], v182, s16, v[154:155]
	v_mad_u64_u32 v[184:185], s[52:53], v184, s16, v[154:155]
	v_mad_u64_u32 v[186:187], s[52:53], v186, s16, v[154:155]
	v_mad_u64_u32 v[188:189], s[52:53], v188, s16, v[154:155]
	v_mad_u64_u32 v[190:191], s[52:53], v190, s16, v[154:155]
	v_mad_u64_u32 v[192:193], s[52:53], v192, s16, v[154:155]
	v_mad_u64_u32 v[194:195], s[52:53], v194, s16, v[154:155]
	v_mad_u64_u32 v[196:197], s[52:53], v196, s16, v[154:155]
	v_mad_u64_u32 v[198:199], s[52:53], v198, s16, v[154:155]
	v_mad_u64_u32 v[200:201], s[52:53], v200, s16, v[154:155]
	v_mad_u64_u32 v[202:203], s[52:53], v202, s16, v[154:155]
	s_waitcnt vmcnt(31)
	ds_write_b32 v24, v11
	s_waitcnt vmcnt(30)
	ds_write_b32 v28, v13
	s_waitcnt vmcnt(29)
	ds_write_b32 v30, v58
	s_waitcnt vmcnt(28)
	ds_write_b32 v32, v59
	s_waitcnt vmcnt(27)
	ds_write_b32 v34, v60
	s_waitcnt vmcnt(26)
	ds_write_b32 v36, v61
	s_waitcnt vmcnt(25)
	ds_write_b32 v38, v62
	s_waitcnt vmcnt(24)
	ds_write_b32 v40, v63
	s_waitcnt vmcnt(23)
	ds_write_b32 v42, v64
	s_waitcnt vmcnt(22)
	ds_write_b32 v44, v65
	s_waitcnt vmcnt(21)
	ds_write_b32 v46, v66
	s_waitcnt vmcnt(20)
	ds_write_b32 v48, v67
	s_waitcnt vmcnt(19)
	ds_write_b32 v50, v6
	s_waitcnt vmcnt(18)
	ds_write_b32 v52, v68
	s_waitcnt vmcnt(17)
	ds_write_b32 v54, v69
	s_waitcnt vmcnt(16)
	ds_write_b32 v56, v70
	s_waitcnt vmcnt(15)
	ds_write_b32 v170, v157
	s_waitcnt vmcnt(14)
	ds_write_b32 v174, v159
	s_waitcnt vmcnt(13)
	ds_write_b32 v176, v204
	s_waitcnt vmcnt(12)
	ds_write_b32 v178, v205
	s_waitcnt vmcnt(11)
	ds_write_b32 v180, v206
	s_waitcnt vmcnt(10)
	ds_write_b32 v182, v207
	s_waitcnt vmcnt(9)
	ds_write_b32 v184, v208
	s_waitcnt vmcnt(8)
	ds_write_b32 v186, v209
	s_waitcnt vmcnt(7)
	ds_write_b32 v188, v210
	s_waitcnt vmcnt(6)
	ds_write_b32 v190, v211
	s_waitcnt vmcnt(5)
	ds_write_b32 v192, v212
	s_waitcnt vmcnt(4)
	ds_write_b32 v194, v213
	s_waitcnt vmcnt(3)
	ds_write_b32 v196, v152
	s_waitcnt vmcnt(2)
	ds_write_b32 v198, v214
	s_waitcnt vmcnt(1)
	ds_write_b32 v200, v215
	s_waitcnt vmcnt(0)
	ds_write_b32 v202, v216
	s_lshl_b64 s[8:9], s[8:9], 1
	s_waitcnt lgkmcnt(0)
	s_add_u32 s8, s14, s8
	ds_read2_b32 v[14:15], v23 offset0:33 offset1:41
	ds_read2_b32 v[24:25], v23 offset1:8
	ds_read2_b32 v[32:33], v23 offset0:66 offset1:74
	ds_read2_b32 v[34:35], v23 offset0:99 offset1:107
	ds_read2_b32 v[36:37], v23 offset0:132 offset1:140
	ds_read2_b32 v[38:39], v23 offset0:165 offset1:173
	ds_read2_b32 v[40:41], v23 offset0:198 offset1:206
	ds_read2_b32 v[42:43], v23 offset0:231 offset1:239
	s_addc_u32 s9, s15, s9
	s_lshl_b32 s11, s11, 1
	s_add_u32 s8, s8, s11
	s_addc_u32 s9, s9, 0
	v_mov_b32_e32 v13, v7
	v_or_b32_e32 v3, s6, v5
	v_lshl_add_u64 v[44:45], s[8:9], 0, v[12:13]
	v_lshlrev_b32_e32 v6, 13, v3
	s_waitcnt lgkmcnt(6)
	v_cvt_pk_bf16_f32 v28, v24, v14
	s_waitcnt lgkmcnt(4)
	v_cvt_pk_bf16_f32 v29, v32, v34
	s_waitcnt lgkmcnt(2)
	v_cvt_pk_bf16_f32 v30, v36, v38
	s_waitcnt lgkmcnt(0)
	v_cvt_pk_bf16_f32 v31, v40, v42
	v_lshl_add_u64 v[46:47], v[44:45], 0, v[6:7]
	global_store_dwordx4 v[46:47], v[28:31], off
	v_or_b32_e32 v3, s6, v9
	v_lshlrev_b32_e32 v6, 13, v3
	v_cvt_pk_bf16_f32 v28, v25, v15
	v_cvt_pk_bf16_f32 v29, v33, v35
	v_cvt_pk_bf16_f32 v30, v37, v39
	v_cvt_pk_bf16_f32 v31, v41, v43
	ds_read2_b32 v[24:25], v23 offset0:49 offset1:57
	ds_read2_b32 v[32:33], v23 offset0:16 offset1:24
	ds_read2_b32 v[34:35], v23 offset0:82 offset1:90
	ds_read2_b32 v[36:37], v23 offset0:115 offset1:123
	ds_read2_b32 v[38:39], v23 offset0:148 offset1:156
	ds_read2_b32 v[40:41], v23 offset0:181 offset1:189
	ds_read2_b32 v[42:43], v23 offset0:214 offset1:222
	ds_read2_b32 v[46:47], v23 offset0:247 offset1:255
	v_or_b32_e32 v3, s6, v17
	v_lshl_add_u64 v[14:15], v[44:45], 0, v[6:7]
	v_lshlrev_b32_e32 v6, 13, v3
	v_or_b32_e32 v3, s6, v18
	global_store_dwordx4 v[14:15], v[28:31], off
	v_lshl_add_u64 v[14:15], v[44:45], 0, v[6:7]
	v_lshlrev_b32_e32 v6, 13, v3
	s_waitcnt lgkmcnt(6)
	v_cvt_pk_bf16_f32 v28, v32, v24
	s_waitcnt lgkmcnt(4)
	v_cvt_pk_bf16_f32 v29, v34, v36
	s_waitcnt lgkmcnt(2)
	v_cvt_pk_bf16_f32 v30, v38, v40
	s_waitcnt lgkmcnt(0)
	v_cvt_pk_bf16_f32 v31, v42, v46
	global_store_dwordx4 v[14:15], v[28:31], off
	v_lshl_add_u64 v[14:15], v[44:45], 0, v[6:7]
	s_mov_b64 s[8:9], 0
	v_cvt_pk_bf16_f32 v28, v33, v25
	v_cvt_pk_bf16_f32 v29, v35, v37
	v_cvt_pk_bf16_f32 v30, v39, v41
	v_cvt_pk_bf16_f32 v31, v43, v47
	global_store_dwordx4 v[14:15], v[28:31], off
	s_waitcnt lgkmcnt(0)

.LBB0_30:
	s_lshl_b32 s51, s11, 1
	s_lshl_b32 s52, s10, 1
	v_or_b32_e32 v6, s52, v16
	s_add_i32 s60, s51, 4
	s_add_i32 s61, s52, 4
	v_mov_b32_e32 v29, v7
	s_add_i32 s63, s52, 8
	v_lshlrev_b64 v[42:43], 14, v[6:7]
	v_or_b32_e32 v28, s60, v3
	v_or_b32_e32 v6, s61, v16
	v_mov_b32_e32 v25, v7
	v_or_b32_e32 v24, s51, v3
	s_add_i32 s65, s52, 12
	v_lshlrev_b64 v[28:29], 14, v[28:29]
	v_lshlrev_b64 v[44:45], 14, v[6:7]
	v_or_b32_e32 v6, s63, v16
	s_add_i32 s62, s51, 8
	s_add_i32 s64, s51, 12
	s_add_i32 s67, s52, 16
	v_lshlrev_b64 v[24:25], 14, v[24:25]
	v_lshl_add_u64 v[42:43], v[14:15], 0, v[42:43]
	v_lshl_add_u64 v[28:29], v[14:15], 0, v[28:29]
	v_lshlrev_b64 v[46:47], 14, v[6:7]
	v_or_b32_e32 v6, s65, v16
	v_mov_b32_e32 v31, v7
	v_mov_b32_e32 v33, v7
	s_add_i32 s69, s52, 20
	v_or_b32_e32 v30, s62, v3
	v_or_b32_e32 v32, s64, v3
	v_lshl_add_u64 v[24:25], v[14:15], 0, v[24:25]
	v_lshl_add_u64 v[44:45], v[14:15], 0, v[44:45]
	global_load_dword v11, v[42:43], off
	global_load_dword v13, v[24:25], off
	global_load_dword v58, v[44:45], off
	global_load_dword v59, v[28:29], off
	v_lshlrev_b64 v[28:29], 14, v[6:7]
	v_or_b32_e32 v6, s67, v16
	s_add_i32 s66, s51, 16
	s_add_i32 s68, s51, 20
	s_add_i32 s71, s52, 24
	v_lshlrev_b64 v[30:31], 14, v[30:31]
	v_lshlrev_b64 v[32:33], 14, v[32:33]
	v_lshl_add_u64 v[24:25], v[14:15], 0, v[46:47]
	v_lshl_add_u64 v[28:29], v[14:15], 0, v[28:29]
	v_lshlrev_b64 v[42:43], 14, v[6:7]
	v_or_b32_e32 v6, s69, v16
	v_mov_b32_e32 v35, v7
	v_mov_b32_e32 v37, v7
	s_add_i32 s70, s51, 24
	s_add_i32 s72, s51, 28
	s_add_i32 s73, s52, 28
	v_or_b32_e32 v34, s66, v3
	v_or_b32_e32 v36, s68, v3
	v_lshl_add_u64 v[30:31], v[14:15], 0, v[30:31]
	v_lshl_add_u64 v[32:33], v[14:15], 0, v[32:33]
	global_load_dword v60, v[24:25], off
	global_load_dword v61, v[30:31], off
	global_load_dword v62, v[28:29], off
	global_load_dword v63, v[32:33], off
	v_lshlrev_b64 v[28:29], 14, v[6:7]
	v_or_b32_e32 v6, s71, v16
	v_mov_b32_e32 v39, v7
	v_mov_b32_e32 v41, v7
	v_or_b32_e32 v38, s70, v3
	v_or_b32_e32 v40, s72, v3
	v_lshlrev_b64 v[34:35], 14, v[34:35]
	v_lshlrev_b64 v[36:37], 14, v[36:37]
	v_lshl_add_u64 v[24:25], v[14:15], 0, v[42:43]
	v_lshl_add_u64 v[28:29], v[14:15], 0, v[28:29]
	v_lshlrev_b64 v[30:31], 14, v[6:7]
	v_or_b32_e32 v6, s73, v16
	v_lshlrev_b64 v[38:39], 14, v[38:39]
	v_lshlrev_b64 v[40:41], 14, v[40:41]
	v_lshl_add_u64 v[34:35], v[14:15], 0, v[34:35]
	v_lshl_add_u64 v[36:37], v[14:15], 0, v[36:37]
	global_load_dword v64, v[24:25], off
	global_load_dword v65, v[34:35], off
	global_load_dword v66, v[28:29], off
	global_load_dword v67, v[36:37], off
	v_lshl_add_u64 v[24:25], v[14:15], 0, v[30:31]
	v_lshlrev_b64 v[28:29], 14, v[6:7]
	v_lshl_add_u64 v[38:39], v[14:15], 0, v[38:39]
	v_lshl_add_u64 v[40:41], v[14:15], 0, v[40:41]
	v_lshl_add_u64 v[28:29], v[14:15], 0, v[28:29]
	global_load_dword v6, v[24:25], off
	global_load_dword v68, v[38:39], off
	global_load_dword v69, v[28:29], off
	global_load_dword v70, v[40:41], off
	v_or_b32_e32 v28, s51, v1
	v_or_b32_e32 v24, s52, v2
	s_add_i32 s10, s10, 16
	s_add_i32 s11, s11, 16
	s_add_i32 s13, s13, -16
	v_mad_u64_u32 v[24:25], s[52:53], v24, s16, v[8:9]
	v_mad_u64_u32 v[28:29], s[52:53], v28, s16, v[8:9]
	v_or_b32_e32 v25, s60, v1
	v_or_b32_e32 v29, s61, v2
	v_or_b32_e32 v36, s62, v1
	v_or_b32_e32 v34, s63, v2
	v_or_b32_e32 v40, s64, v1
	v_or_b32_e32 v38, s65, v2
	v_or_b32_e32 v44, s66, v1
	v_or_b32_e32 v42, s67, v2
	v_or_b32_e32 v48, s68, v1
	v_or_b32_e32 v46, s69, v2
	v_or_b32_e32 v52, s70, v1
	v_or_b32_e32 v50, s71, v2
	v_or_b32_e32 v56, s72, v1
	v_or_b32_e32 v54, s73, v2
	v_mad_u64_u32 v[30:31], s[52:53], v29, s16, v[8:9]
	v_mad_u64_u32 v[32:33], s[52:53], v25, s16, v[8:9]
	v_mad_u64_u32 v[34:35], s[52:53], v34, s16, v[8:9]
	v_mad_u64_u32 v[36:37], s[52:53], v36, s16, v[8:9]
	v_mad_u64_u32 v[38:39], s[52:53], v38, s16, v[8:9]
	v_mad_u64_u32 v[40:41], s[52:53], v40, s16, v[8:9]
	v_mad_u64_u32 v[42:43], s[52:53], v42, s16, v[8:9]
	v_mad_u64_u32 v[44:45], s[52:53], v44, s16, v[8:9]
	v_mad_u64_u32 v[46:47], s[52:53], v46, s16, v[8:9]
	v_mad_u64_u32 v[48:49], s[52:53], v48, s16, v[8:9]
	v_mad_u64_u32 v[50:51], s[52:53], v50, s16, v[8:9]
	v_mad_u64_u32 v[52:53], s[52:53], v52, s16, v[8:9]
	v_mad_u64_u32 v[54:55], s[52:53], v54, s16, v[8:9]
	v_mad_u64_u32 v[56:57], s[52:53], v56, s16, v[8:9]
	v_mov_b32_e32 v147, v1
	v_mov_b32_e32 v148, v2
	v_mov_b32_e32 v149, v3
	v_mov_b32_e32 v153, v7
	v_mov_b32_e32 v154, v8
	v_mov_b32_e32 v155, v9
	v_mov_b32_e32 v160, v14
	v_mov_b32_e32 v161, v15
	v_mov_b32_e32 v162, v16
	s_lshl_b32 s51, s11, 1
	s_lshl_b32 s52, s10, 1
	v_or_b32_e32 v152, s52, v162
	s_add_i32 s60, s51, 4
	s_add_i32 s61, s52, 4
	v_mov_b32_e32 v175, v153
	s_add_i32 s63, s52, 8
	v_lshlrev_b64 v[188:189], 14, v[152:153]
	v_or_b32_e32 v174, s60, v149
	v_or_b32_e32 v152, s61, v162
	v_mov_b32_e32 v171, v153
	v_or_b32_e32 v170, s51, v149
	s_add_i32 s65, s52, 12
	v_lshlrev_b64 v[174:175], 14, v[174:175]
	v_lshlrev_b64 v[190:191], 14, v[152:153]
	v_or_b32_e32 v152, s63, v162
	s_add_i32 s62, s51, 8
	s_add_i32 s64, s51, 12
	s_add_i32 s67, s52, 16
	v_lshlrev_b64 v[170:171], 14, v[170:171]
	v_lshl_add_u64 v[188:189], v[160:161], 0, v[188:189]
	v_lshl_add_u64 v[174:175], v[160:161], 0, v[174:175]
	v_lshlrev_b64 v[192:193], 14, v[152:153]
	v_or_b32_e32 v152, s65, v162
	v_mov_b32_e32 v177, v153
	v_mov_b32_e32 v179, v153
	s_add_i32 s69, s52, 20
	v_or_b32_e32 v176, s62, v149
	v_or_b32_e32 v178, s64, v149
	v_lshl_add_u64 v[170:171], v[160:161], 0, v[170:171]
	v_lshl_add_u64 v[190:191], v[160:161], 0, v[190:191]
	global_load_dword v157, v[188:189], off
	global_load_dword v159, v[170:171], off
	global_load_dword v204, v[190:191], off
	global_load_dword v205, v[174:175], off
	v_lshlrev_b64 v[174:175], 14, v[152:153]
	v_or_b32_e32 v152, s67, v162
	s_add_i32 s66, s51, 16
	s_add_i32 s68, s51, 20
	s_add_i32 s71, s52, 24
	v_lshlrev_b64 v[176:177], 14, v[176:177]
	v_lshlrev_b64 v[178:179], 14, v[178:179]
	v_lshl_add_u64 v[170:171], v[160:161], 0, v[192:193]
	v_lshl_add_u64 v[174:175], v[160:161], 0, v[174:175]
	v_lshlrev_b64 v[188:189], 14, v[152:153]
	v_or_b32_e32 v152, s69, v162
	v_mov_b32_e32 v181, v153
	v_mov_b32_e32 v183, v153
	s_add_i32 s70, s51, 24
	s_add_i32 s72, s51, 28
	s_add_i32 s73, s52, 28
	v_or_b32_e32 v180, s66, v149
	v_or_b32_e32 v182, s68, v149
	v_lshl_add_u64 v[176:177], v[160:161], 0, v[176:177]
	v_lshl_add_u64 v[178:179], v[160:161], 0, v[178:179]
	global_load_dword v206, v[170:171], off
	global_load_dword v207, v[176:177], off
	global_load_dword v208, v[174:175], off
	global_load_dword v209, v[178:179], off
	v_lshlrev_b64 v[174:175], 14, v[152:153]
	v_or_b32_e32 v152, s71, v162
	v_mov_b32_e32 v185, v153
	v_mov_b32_e32 v187, v153
	v_or_b32_e32 v184, s70, v149
	v_or_b32_e32 v186, s72, v149
	v_lshlrev_b64 v[180:181], 14, v[180:181]
	v_lshlrev_b64 v[182:183], 14, v[182:183]
	v_lshl_add_u64 v[170:171], v[160:161], 0, v[188:189]
	v_lshl_add_u64 v[174:175], v[160:161], 0, v[174:175]
	v_lshlrev_b64 v[176:177], 14, v[152:153]
	v_or_b32_e32 v152, s73, v162
	v_lshlrev_b64 v[184:185], 14, v[184:185]
	v_lshlrev_b64 v[186:187], 14, v[186:187]
	v_lshl_add_u64 v[180:181], v[160:161], 0, v[180:181]
	v_lshl_add_u64 v[182:183], v[160:161], 0, v[182:183]
	global_load_dword v210, v[170:171], off
	global_load_dword v211, v[180:181], off
	global_load_dword v212, v[174:175], off
	global_load_dword v213, v[182:183], off
	v_lshl_add_u64 v[170:171], v[160:161], 0, v[176:177]
	v_lshlrev_b64 v[174:175], 14, v[152:153]
	v_lshl_add_u64 v[184:185], v[160:161], 0, v[184:185]
	v_lshl_add_u64 v[186:187], v[160:161], 0, v[186:187]
	v_lshl_add_u64 v[174:175], v[160:161], 0, v[174:175]
	global_load_dword v152, v[170:171], off
	global_load_dword v214, v[184:185], off
	global_load_dword v215, v[174:175], off
	global_load_dword v216, v[186:187], off
	v_or_b32_e32 v174, s51, v147
	v_or_b32_e32 v170, s52, v148
	s_add_i32 s10, s10, 16
	s_add_i32 s11, s11, 16
	s_add_i32 s13, s13, -16
	v_mad_u64_u32 v[170:171], s[52:53], v170, s16, v[154:155]
	v_mad_u64_u32 v[174:175], s[52:53], v174, s16, v[154:155]
	v_or_b32_e32 v171, s60, v147
	v_or_b32_e32 v175, s61, v148
	v_or_b32_e32 v182, s62, v147
	v_or_b32_e32 v180, s63, v148
	v_or_b32_e32 v186, s64, v147
	v_or_b32_e32 v184, s65, v148
	v_or_b32_e32 v190, s66, v147
	v_or_b32_e32 v188, s67, v148
	v_or_b32_e32 v194, s68, v147
	v_or_b32_e32 v192, s69, v148
	v_or_b32_e32 v198, s70, v147
	v_or_b32_e32 v196, s71, v148
	v_or_b32_e32 v202, s72, v147
	v_or_b32_e32 v200, s73, v148
	v_mad_u64_u32 v[176:177], s[52:53], v175, s16, v[154:155]
	v_mad_u64_u32 v[178:179], s[52:53], v171, s16, v[154:155]
	v_mad_u64_u32 v[180:181], s[52:53], v180, s16, v[154:155]
	v_mad_u64_u32 v[182:183], s[52:53], v182, s16, v[154:155]
	v_mad_u64_u32 v[184:185], s[52:53], v184, s16, v[154:155]
	v_mad_u64_u32 v[186:187], s[52:53], v186, s16, v[154:155]
	v_mad_u64_u32 v[188:189], s[52:53], v188, s16, v[154:155]
	v_mad_u64_u32 v[190:191], s[52:53], v190, s16, v[154:155]
	v_mad_u64_u32 v[192:193], s[52:53], v192, s16, v[154:155]
	v_mad_u64_u32 v[194:195], s[52:53], v194, s16, v[154:155]
	v_mad_u64_u32 v[196:197], s[52:53], v196, s16, v[154:155]
	v_mad_u64_u32 v[198:199], s[52:53], v198, s16, v[154:155]
	v_mad_u64_u32 v[200:201], s[52:53], v200, s16, v[154:155]
	v_mad_u64_u32 v[202:203], s[52:53], v202, s16, v[154:155]
	s_waitcnt vmcnt(31)
	ds_write_b32 v24, v11
	s_waitcnt vmcnt(30)
	ds_write_b32 v28, v13
	s_waitcnt vmcnt(29)
	ds_write_b32 v30, v58
	s_waitcnt vmcnt(28)
	ds_write_b32 v32, v59
	s_waitcnt vmcnt(27)
	ds_write_b32 v34, v60
	s_waitcnt vmcnt(26)
	ds_write_b32 v36, v61
	s_waitcnt vmcnt(25)
	ds_write_b32 v38, v62
	s_waitcnt vmcnt(24)
	ds_write_b32 v40, v63
	s_waitcnt vmcnt(23)
	ds_write_b32 v42, v64
	s_waitcnt vmcnt(22)
	ds_write_b32 v44, v65
	s_waitcnt vmcnt(21)
	ds_write_b32 v46, v66
	s_waitcnt vmcnt(20)
	ds_write_b32 v48, v67
	s_waitcnt vmcnt(19)
	ds_write_b32 v50, v6
	s_waitcnt vmcnt(18)
	ds_write_b32 v52, v68
	s_waitcnt vmcnt(17)
	ds_write_b32 v54, v69
	s_waitcnt vmcnt(16)
	ds_write_b32 v56, v70
	s_waitcnt vmcnt(15)
	ds_write_b32 v170, v157
	s_waitcnt vmcnt(14)
	ds_write_b32 v174, v159
	s_waitcnt vmcnt(13)
	ds_write_b32 v176, v204
	s_waitcnt vmcnt(12)
	ds_write_b32 v178, v205
	s_waitcnt vmcnt(11)
	ds_write_b32 v180, v206
	s_waitcnt vmcnt(10)
	ds_write_b32 v182, v207
	s_waitcnt vmcnt(9)
	ds_write_b32 v184, v208
	s_waitcnt vmcnt(8)
	ds_write_b32 v186, v209
	s_waitcnt vmcnt(7)
	ds_write_b32 v188, v210
	s_waitcnt vmcnt(6)
	ds_write_b32 v190, v211
	s_waitcnt vmcnt(5)
	ds_write_b32 v192, v212
	s_waitcnt vmcnt(4)
	ds_write_b32 v194, v213
	s_waitcnt vmcnt(3)
	ds_write_b32 v196, v152
	s_waitcnt vmcnt(2)
	ds_write_b32 v198, v214
	s_waitcnt vmcnt(1)
	ds_write_b32 v200, v215
	s_waitcnt vmcnt(0)
	ds_write_b32 v202, v216
	s_lshl_b64 s[8:9], s[8:9], 1
	s_waitcnt lgkmcnt(0)
	s_add_u32 s8, s17, s8
	ds_read2_b32 v[14:15], v23 offset0:33 offset1:41
	ds_read2_b32 v[24:25], v23 offset1:8
	ds_read2_b32 v[32:33], v23 offset0:66 offset1:74
	ds_read2_b32 v[34:35], v23 offset0:99 offset1:107
	ds_read2_b32 v[36:37], v23 offset0:132 offset1:140
	ds_read2_b32 v[38:39], v23 offset0:165 offset1:173
	ds_read2_b32 v[40:41], v23 offset0:198 offset1:206
	ds_read2_b32 v[42:43], v23 offset0:231 offset1:239
	s_addc_u32 s9, s18, s9
	s_lshl_b32 s10, s12, 1
	s_add_u32 s8, s8, s10
	s_addc_u32 s9, s9, 0
	v_mov_b32_e32 v13, v7
	v_or_b32_e32 v3, s6, v5
	v_lshl_add_u64 v[44:45], s[8:9], 0, v[12:13]
	v_lshlrev_b32_e32 v6, 11, v3
	s_waitcnt lgkmcnt(6)
	v_cvt_pk_bf16_f32 v28, v24, v14
	s_waitcnt lgkmcnt(4)
	v_cvt_pk_bf16_f32 v29, v32, v34
	s_waitcnt lgkmcnt(2)
	v_cvt_pk_bf16_f32 v30, v36, v38
	s_waitcnt lgkmcnt(0)
	v_cvt_pk_bf16_f32 v31, v40, v42
	v_lshl_add_u64 v[46:47], v[44:45], 0, v[6:7]
	global_store_dwordx4 v[46:47], v[28:31], off
	v_or_b32_e32 v3, s6, v9
	v_lshlrev_b32_e32 v6, 11, v3
	v_cvt_pk_bf16_f32 v28, v25, v15
	v_cvt_pk_bf16_f32 v29, v33, v35
	v_cvt_pk_bf16_f32 v30, v37, v39
	v_cvt_pk_bf16_f32 v31, v41, v43
	ds_read2_b32 v[24:25], v23 offset0:49 offset1:57
	ds_read2_b32 v[32:33], v23 offset0:16 offset1:24
	ds_read2_b32 v[34:35], v23 offset0:82 offset1:90
	ds_read2_b32 v[36:37], v23 offset0:115 offset1:123
	ds_read2_b32 v[38:39], v23 offset0:148 offset1:156
	ds_read2_b32 v[40:41], v23 offset0:181 offset1:189
	ds_read2_b32 v[42:43], v23 offset0:214 offset1:222
	ds_read2_b32 v[46:47], v23 offset0:247 offset1:255
	v_or_b32_e32 v3, s6, v17
	v_lshl_add_u64 v[14:15], v[44:45], 0, v[6:7]
	v_lshlrev_b32_e32 v6, 11, v3
	v_or_b32_e32 v3, s6, v18
	global_store_dwordx4 v[14:15], v[28:31], off
	v_lshl_add_u64 v[14:15], v[44:45], 0, v[6:7]
	v_lshlrev_b32_e32 v6, 11, v3
	s_waitcnt lgkmcnt(6)
	v_cvt_pk_bf16_f32 v28, v32, v24
	s_waitcnt lgkmcnt(4)
	v_cvt_pk_bf16_f32 v29, v34, v36
	s_waitcnt lgkmcnt(2)
	v_cvt_pk_bf16_f32 v30, v38, v40
	s_waitcnt lgkmcnt(0)
	v_cvt_pk_bf16_f32 v31, v42, v46
	global_store_dwordx4 v[14:15], v[28:31], off
	v_lshl_add_u64 v[14:15], v[44:45], 0, v[6:7]
	s_nop 0
	v_cvt_pk_bf16_f32 v28, v33, v25
	v_cvt_pk_bf16_f32 v29, v35, v37
	v_cvt_pk_bf16_f32 v30, v39, v41
	v_cvt_pk_bf16_f32 v31, v43, v47
	global_store_dwordx4 v[14:15], v[28:31], off
	s_waitcnt lgkmcnt(0)

.LBB0_35:
	s_lshl_b32 s51, s11, 1
	s_lshl_b32 s52, s12, 1
	v_or_b32_e32 v6, s52, v16
	s_add_i32 s60, s51, 4
	s_add_i32 s61, s52, 4
	v_mov_b32_e32 v29, v7
	s_add_i32 s63, s52, 8
	v_lshlrev_b64 v[42:43], 12, v[6:7]
	v_or_b32_e32 v28, s60, v3
	v_or_b32_e32 v6, s61, v16
	v_mov_b32_e32 v25, v7
	v_or_b32_e32 v24, s51, v3
	s_add_i32 s65, s52, 12
	v_lshlrev_b64 v[28:29], 12, v[28:29]
	v_lshlrev_b64 v[44:45], 12, v[6:7]
	v_or_b32_e32 v6, s63, v16
	s_add_i32 s62, s51, 8
	s_add_i32 s64, s51, 12
	s_add_i32 s67, s52, 16
	v_lshlrev_b64 v[24:25], 12, v[24:25]
	v_lshl_add_u64 v[42:43], v[14:15], 0, v[42:43]
	v_lshl_add_u64 v[28:29], v[14:15], 0, v[28:29]
	v_lshlrev_b64 v[46:47], 12, v[6:7]
	v_or_b32_e32 v6, s65, v16
	v_mov_b32_e32 v31, v7
	v_mov_b32_e32 v33, v7
	s_add_i32 s69, s52, 20
	v_or_b32_e32 v30, s62, v3
	v_or_b32_e32 v32, s64, v3
	v_lshl_add_u64 v[24:25], v[14:15], 0, v[24:25]
	v_lshl_add_u64 v[44:45], v[14:15], 0, v[44:45]
	global_load_dword v11, v[42:43], off
	global_load_dword v13, v[24:25], off
	global_load_dword v58, v[44:45], off
	global_load_dword v59, v[28:29], off
	v_lshlrev_b64 v[28:29], 12, v[6:7]
	v_or_b32_e32 v6, s67, v16
	s_add_i32 s66, s51, 16
	s_add_i32 s68, s51, 20
	s_add_i32 s71, s52, 24
	v_lshlrev_b64 v[30:31], 12, v[30:31]
	v_lshlrev_b64 v[32:33], 12, v[32:33]
	v_lshl_add_u64 v[24:25], v[14:15], 0, v[46:47]
	v_lshl_add_u64 v[28:29], v[14:15], 0, v[28:29]
	v_lshlrev_b64 v[42:43], 12, v[6:7]
	v_or_b32_e32 v6, s69, v16
	v_mov_b32_e32 v35, v7
	v_mov_b32_e32 v37, v7
	s_add_i32 s70, s51, 24
	s_add_i32 s72, s51, 28
	s_add_i32 s73, s52, 28
	v_or_b32_e32 v34, s66, v3
	v_or_b32_e32 v36, s68, v3
	v_lshl_add_u64 v[30:31], v[14:15], 0, v[30:31]
	v_lshl_add_u64 v[32:33], v[14:15], 0, v[32:33]
	global_load_dword v60, v[24:25], off
	global_load_dword v61, v[30:31], off
	global_load_dword v62, v[28:29], off
	global_load_dword v63, v[32:33], off
	v_lshlrev_b64 v[28:29], 12, v[6:7]
	v_or_b32_e32 v6, s71, v16
	v_mov_b32_e32 v39, v7
	v_mov_b32_e32 v41, v7
	v_or_b32_e32 v38, s70, v3
	v_or_b32_e32 v40, s72, v3
	v_lshlrev_b64 v[34:35], 12, v[34:35]
	v_lshlrev_b64 v[36:37], 12, v[36:37]
	v_lshl_add_u64 v[24:25], v[14:15], 0, v[42:43]
	v_lshl_add_u64 v[28:29], v[14:15], 0, v[28:29]
	v_lshlrev_b64 v[30:31], 12, v[6:7]
	v_or_b32_e32 v6, s73, v16
	v_lshlrev_b64 v[38:39], 12, v[38:39]
	v_lshlrev_b64 v[40:41], 12, v[40:41]
	v_lshl_add_u64 v[34:35], v[14:15], 0, v[34:35]
	v_lshl_add_u64 v[36:37], v[14:15], 0, v[36:37]
	global_load_dword v64, v[24:25], off
	global_load_dword v65, v[34:35], off
	global_load_dword v66, v[28:29], off
	global_load_dword v67, v[36:37], off
	v_lshl_add_u64 v[24:25], v[14:15], 0, v[30:31]
	v_lshlrev_b64 v[28:29], 12, v[6:7]
	v_lshl_add_u64 v[38:39], v[14:15], 0, v[38:39]
	v_lshl_add_u64 v[40:41], v[14:15], 0, v[40:41]
	v_lshl_add_u64 v[28:29], v[14:15], 0, v[28:29]
	global_load_dword v6, v[24:25], off
	global_load_dword v68, v[38:39], off
	global_load_dword v69, v[28:29], off
	global_load_dword v70, v[40:41], off
	v_or_b32_e32 v28, s51, v1
	v_or_b32_e32 v24, s52, v2
	s_add_i32 s12, s12, 16
	s_add_i32 s11, s11, 16
	s_add_i32 s13, s13, -16
	v_mad_u64_u32 v[24:25], s[52:53], v24, s16, v[8:9]
	v_mad_u64_u32 v[28:29], s[52:53], v28, s16, v[8:9]
	v_or_b32_e32 v25, s60, v1
	v_or_b32_e32 v29, s61, v2
	v_or_b32_e32 v36, s62, v1
	v_or_b32_e32 v34, s63, v2
	v_or_b32_e32 v40, s64, v1
	v_or_b32_e32 v38, s65, v2
	v_or_b32_e32 v44, s66, v1
	v_or_b32_e32 v42, s67, v2
	v_or_b32_e32 v48, s68, v1
	v_or_b32_e32 v46, s69, v2
	v_or_b32_e32 v52, s70, v1
	v_or_b32_e32 v50, s71, v2
	v_or_b32_e32 v56, s72, v1
	v_or_b32_e32 v54, s73, v2
	v_mad_u64_u32 v[30:31], s[52:53], v29, s16, v[8:9]
	v_mad_u64_u32 v[32:33], s[52:53], v25, s16, v[8:9]
	v_mad_u64_u32 v[34:35], s[52:53], v34, s16, v[8:9]
	v_mad_u64_u32 v[36:37], s[52:53], v36, s16, v[8:9]
	v_mad_u64_u32 v[38:39], s[52:53], v38, s16, v[8:9]
	v_mad_u64_u32 v[40:41], s[52:53], v40, s16, v[8:9]
	v_mad_u64_u32 v[42:43], s[52:53], v42, s16, v[8:9]
	v_mad_u64_u32 v[44:45], s[52:53], v44, s16, v[8:9]
	v_mad_u64_u32 v[46:47], s[52:53], v46, s16, v[8:9]
	v_mad_u64_u32 v[48:49], s[52:53], v48, s16, v[8:9]
	v_mad_u64_u32 v[50:51], s[52:53], v50, s16, v[8:9]
	v_mad_u64_u32 v[52:53], s[52:53], v52, s16, v[8:9]
	v_mad_u64_u32 v[54:55], s[52:53], v54, s16, v[8:9]
	v_mad_u64_u32 v[56:57], s[52:53], v56, s16, v[8:9]
	v_mov_b32_e32 v147, v1
	v_mov_b32_e32 v148, v2
	v_mov_b32_e32 v149, v3
	v_mov_b32_e32 v153, v7
	v_mov_b32_e32 v154, v8
	v_mov_b32_e32 v155, v9
	v_mov_b32_e32 v160, v14
	v_mov_b32_e32 v161, v15
	v_mov_b32_e32 v162, v16
	s_lshl_b32 s51, s11, 1
	s_lshl_b32 s52, s12, 1
	v_or_b32_e32 v152, s52, v162
	s_add_i32 s60, s51, 4
	s_add_i32 s61, s52, 4
	v_mov_b32_e32 v175, v153
	s_add_i32 s63, s52, 8
	v_lshlrev_b64 v[188:189], 12, v[152:153]
	v_or_b32_e32 v174, s60, v149
	v_or_b32_e32 v152, s61, v162
	v_mov_b32_e32 v171, v153
	v_or_b32_e32 v170, s51, v149
	s_add_i32 s65, s52, 12
	v_lshlrev_b64 v[174:175], 12, v[174:175]
	v_lshlrev_b64 v[190:191], 12, v[152:153]
	v_or_b32_e32 v152, s63, v162
	s_add_i32 s62, s51, 8
	s_add_i32 s64, s51, 12
	s_add_i32 s67, s52, 16
	v_lshlrev_b64 v[170:171], 12, v[170:171]
	v_lshl_add_u64 v[188:189], v[160:161], 0, v[188:189]
	v_lshl_add_u64 v[174:175], v[160:161], 0, v[174:175]
	v_lshlrev_b64 v[192:193], 12, v[152:153]
	v_or_b32_e32 v152, s65, v162
	v_mov_b32_e32 v177, v153
	v_mov_b32_e32 v179, v153
	s_add_i32 s69, s52, 20
	v_or_b32_e32 v176, s62, v149
	v_or_b32_e32 v178, s64, v149
	v_lshl_add_u64 v[170:171], v[160:161], 0, v[170:171]
	v_lshl_add_u64 v[190:191], v[160:161], 0, v[190:191]
	global_load_dword v157, v[188:189], off
	global_load_dword v159, v[170:171], off
	global_load_dword v204, v[190:191], off
	global_load_dword v205, v[174:175], off
	v_lshlrev_b64 v[174:175], 12, v[152:153]
	v_or_b32_e32 v152, s67, v162
	s_add_i32 s66, s51, 16
	s_add_i32 s68, s51, 20
	s_add_i32 s71, s52, 24
	v_lshlrev_b64 v[176:177], 12, v[176:177]
	v_lshlrev_b64 v[178:179], 12, v[178:179]
	v_lshl_add_u64 v[170:171], v[160:161], 0, v[192:193]
	v_lshl_add_u64 v[174:175], v[160:161], 0, v[174:175]
	v_lshlrev_b64 v[188:189], 12, v[152:153]
	v_or_b32_e32 v152, s69, v162
	v_mov_b32_e32 v181, v153
	v_mov_b32_e32 v183, v153
	s_add_i32 s70, s51, 24
	s_add_i32 s72, s51, 28
	s_add_i32 s73, s52, 28
	v_or_b32_e32 v180, s66, v149
	v_or_b32_e32 v182, s68, v149
	v_lshl_add_u64 v[176:177], v[160:161], 0, v[176:177]
	v_lshl_add_u64 v[178:179], v[160:161], 0, v[178:179]
	global_load_dword v206, v[170:171], off
	global_load_dword v207, v[176:177], off
	global_load_dword v208, v[174:175], off
	global_load_dword v209, v[178:179], off
	v_lshlrev_b64 v[174:175], 12, v[152:153]
	v_or_b32_e32 v152, s71, v162
	v_mov_b32_e32 v185, v153
	v_mov_b32_e32 v187, v153
	v_or_b32_e32 v184, s70, v149
	v_or_b32_e32 v186, s72, v149
	v_lshlrev_b64 v[180:181], 12, v[180:181]
	v_lshlrev_b64 v[182:183], 12, v[182:183]
	v_lshl_add_u64 v[170:171], v[160:161], 0, v[188:189]
	v_lshl_add_u64 v[174:175], v[160:161], 0, v[174:175]
	v_lshlrev_b64 v[176:177], 12, v[152:153]
	v_or_b32_e32 v152, s73, v162
	v_lshlrev_b64 v[184:185], 12, v[184:185]
	v_lshlrev_b64 v[186:187], 12, v[186:187]
	v_lshl_add_u64 v[180:181], v[160:161], 0, v[180:181]
	v_lshl_add_u64 v[182:183], v[160:161], 0, v[182:183]
	global_load_dword v210, v[170:171], off
	global_load_dword v211, v[180:181], off
	global_load_dword v212, v[174:175], off
	global_load_dword v213, v[182:183], off
	v_lshl_add_u64 v[170:171], v[160:161], 0, v[176:177]
	v_lshlrev_b64 v[174:175], 12, v[152:153]
	v_lshl_add_u64 v[184:185], v[160:161], 0, v[184:185]
	v_lshl_add_u64 v[186:187], v[160:161], 0, v[186:187]
	v_lshl_add_u64 v[174:175], v[160:161], 0, v[174:175]
	global_load_dword v152, v[170:171], off
	global_load_dword v214, v[184:185], off
	global_load_dword v215, v[174:175], off
	global_load_dword v216, v[186:187], off
	v_or_b32_e32 v174, s51, v147
	v_or_b32_e32 v170, s52, v148
	s_add_i32 s12, s12, 16
	s_add_i32 s11, s11, 16
	s_add_i32 s13, s13, -16
	v_mad_u64_u32 v[170:171], s[52:53], v170, s16, v[154:155]
	v_mad_u64_u32 v[174:175], s[52:53], v174, s16, v[154:155]
	v_or_b32_e32 v171, s60, v147
	v_or_b32_e32 v175, s61, v148
	v_or_b32_e32 v182, s62, v147
	v_or_b32_e32 v180, s63, v148
	v_or_b32_e32 v186, s64, v147
	v_or_b32_e32 v184, s65, v148
	v_or_b32_e32 v190, s66, v147
	v_or_b32_e32 v188, s67, v148
	v_or_b32_e32 v194, s68, v147
	v_or_b32_e32 v192, s69, v148
	v_or_b32_e32 v198, s70, v147
	v_or_b32_e32 v196, s71, v148
	v_or_b32_e32 v202, s72, v147
	v_or_b32_e32 v200, s73, v148
	v_mad_u64_u32 v[176:177], s[52:53], v175, s16, v[154:155]
	v_mad_u64_u32 v[178:179], s[52:53], v171, s16, v[154:155]
	v_mad_u64_u32 v[180:181], s[52:53], v180, s16, v[154:155]
	v_mad_u64_u32 v[182:183], s[52:53], v182, s16, v[154:155]
	v_mad_u64_u32 v[184:185], s[52:53], v184, s16, v[154:155]
	v_mad_u64_u32 v[186:187], s[52:53], v186, s16, v[154:155]
	v_mad_u64_u32 v[188:189], s[52:53], v188, s16, v[154:155]
	v_mad_u64_u32 v[190:191], s[52:53], v190, s16, v[154:155]
	v_mad_u64_u32 v[192:193], s[52:53], v192, s16, v[154:155]
	v_mad_u64_u32 v[194:195], s[52:53], v194, s16, v[154:155]
	v_mad_u64_u32 v[196:197], s[52:53], v196, s16, v[154:155]
	v_mad_u64_u32 v[198:199], s[52:53], v198, s16, v[154:155]
	v_mad_u64_u32 v[200:201], s[52:53], v200, s16, v[154:155]
	v_mad_u64_u32 v[202:203], s[52:53], v202, s16, v[154:155]
	s_waitcnt vmcnt(31)
	ds_write_b32 v24, v11
	s_waitcnt vmcnt(30)
	ds_write_b32 v28, v13
	s_waitcnt vmcnt(29)
	ds_write_b32 v30, v58
	s_waitcnt vmcnt(28)
	ds_write_b32 v32, v59
	s_waitcnt vmcnt(27)
	ds_write_b32 v34, v60
	s_waitcnt vmcnt(26)
	ds_write_b32 v36, v61
	s_waitcnt vmcnt(25)
	ds_write_b32 v38, v62
	s_waitcnt vmcnt(24)
	ds_write_b32 v40, v63
	s_waitcnt vmcnt(23)
	ds_write_b32 v42, v64
	s_waitcnt vmcnt(22)
	ds_write_b32 v44, v65
	s_waitcnt vmcnt(21)
	ds_write_b32 v46, v66
	s_waitcnt vmcnt(20)
	ds_write_b32 v48, v67
	s_waitcnt vmcnt(19)
	ds_write_b32 v50, v6
	s_waitcnt vmcnt(18)
	ds_write_b32 v52, v68
	s_waitcnt vmcnt(17)
	ds_write_b32 v54, v69
	s_waitcnt vmcnt(16)
	ds_write_b32 v56, v70
	s_waitcnt vmcnt(15)
	ds_write_b32 v170, v157
	s_waitcnt vmcnt(14)
	ds_write_b32 v174, v159
	s_waitcnt vmcnt(13)
	ds_write_b32 v176, v204
	s_waitcnt vmcnt(12)
	ds_write_b32 v178, v205
	s_waitcnt vmcnt(11)
	ds_write_b32 v180, v206
	s_waitcnt vmcnt(10)
	ds_write_b32 v182, v207
	s_waitcnt vmcnt(9)
	ds_write_b32 v184, v208
	s_waitcnt vmcnt(8)
	ds_write_b32 v186, v209
	s_waitcnt vmcnt(7)
	ds_write_b32 v188, v210
	s_waitcnt vmcnt(6)
	ds_write_b32 v190, v211
	s_waitcnt vmcnt(5)
	ds_write_b32 v192, v212
	s_waitcnt vmcnt(4)
	ds_write_b32 v194, v213
	s_waitcnt vmcnt(3)
	ds_write_b32 v196, v152
	s_waitcnt vmcnt(2)
	ds_write_b32 v198, v214
	s_waitcnt vmcnt(1)
	ds_write_b32 v200, v215
	s_waitcnt vmcnt(0)
	ds_write_b32 v202, v216
	s_lshl_b64 s[8:9], s[8:9], 1
	s_waitcnt lgkmcnt(0)
	s_add_u32 s8, s19, s8
	ds_read2_b32 v[14:15], v23 offset0:33 offset1:41
	ds_read2_b32 v[24:25], v23 offset1:8
	ds_read2_b32 v[32:33], v23 offset0:66 offset1:74
	ds_read2_b32 v[34:35], v23 offset0:99 offset1:107
	ds_read2_b32 v[36:37], v23 offset0:132 offset1:140
	ds_read2_b32 v[38:39], v23 offset0:165 offset1:173
	ds_read2_b32 v[40:41], v23 offset0:198 offset1:206
	ds_read2_b32 v[42:43], v23 offset0:231 offset1:239
	s_addc_u32 s9, s20, s9
	s_lshl_b32 s10, s10, 1
	s_add_u32 s8, s8, s10
	s_addc_u32 s9, s9, 0
	v_mov_b32_e32 v13, v7
	v_or_b32_e32 v3, s6, v5
	v_lshl_add_u64 v[44:45], s[8:9], 0, v[12:13]
	v_lshlrev_b32_e32 v6, 12, v3
	s_waitcnt lgkmcnt(6)
	v_cvt_pk_bf16_f32 v28, v24, v14
	s_waitcnt lgkmcnt(4)
	v_cvt_pk_bf16_f32 v29, v32, v34
	s_waitcnt lgkmcnt(2)
	v_cvt_pk_bf16_f32 v30, v36, v38
	s_waitcnt lgkmcnt(0)
	v_cvt_pk_bf16_f32 v31, v40, v42
	v_lshl_add_u64 v[46:47], v[44:45], 0, v[6:7]
	global_store_dwordx4 v[46:47], v[28:31], off
	v_or_b32_e32 v3, s6, v9
	v_lshlrev_b32_e32 v6, 12, v3
	v_cvt_pk_bf16_f32 v28, v25, v15
	v_cvt_pk_bf16_f32 v29, v33, v35
	v_cvt_pk_bf16_f32 v30, v37, v39
	v_cvt_pk_bf16_f32 v31, v41, v43
	ds_read2_b32 v[24:25], v23 offset0:49 offset1:57
	ds_read2_b32 v[32:33], v23 offset0:16 offset1:24
	ds_read2_b32 v[34:35], v23 offset0:82 offset1:90
	ds_read2_b32 v[36:37], v23 offset0:115 offset1:123
	ds_read2_b32 v[38:39], v23 offset0:148 offset1:156
	ds_read2_b32 v[40:41], v23 offset0:181 offset1:189
	ds_read2_b32 v[42:43], v23 offset0:214 offset1:222
	ds_read2_b32 v[46:47], v23 offset0:247 offset1:255
	v_or_b32_e32 v3, s6, v17
	v_lshl_add_u64 v[14:15], v[44:45], 0, v[6:7]
	v_lshlrev_b32_e32 v6, 12, v3
	v_or_b32_e32 v3, s6, v18
	global_store_dwordx4 v[14:15], v[28:31], off
	v_lshl_add_u64 v[14:15], v[44:45], 0, v[6:7]
	v_lshlrev_b32_e32 v6, 12, v3
	s_waitcnt lgkmcnt(6)
	v_cvt_pk_bf16_f32 v28, v32, v24
	s_waitcnt lgkmcnt(4)
	v_cvt_pk_bf16_f32 v29, v34, v36
	s_waitcnt lgkmcnt(2)
	v_cvt_pk_bf16_f32 v30, v38, v40
	s_waitcnt lgkmcnt(0)
	v_cvt_pk_bf16_f32 v31, v42, v46
	global_store_dwordx4 v[14:15], v[28:31], off
	v_lshl_add_u64 v[14:15], v[44:45], 0, v[6:7]
	s_nop 0
	v_cvt_pk_bf16_f32 v28, v33, v25
	v_cvt_pk_bf16_f32 v29, v35, v37
	v_cvt_pk_bf16_f32 v30, v39, v41
	v_cvt_pk_bf16_f32 v31, v43, v47
	global_store_dwordx4 v[14:15], v[28:31], off
	s_waitcnt lgkmcnt(0)

.LBB0_40:
	s_lshl_b32 s60, s52, 1
	s_lshl_b32 s61, s12, 1
	v_or_b32_e32 v3, s60, v1
	v_or_b32_e32 v11, s61, v2
	s_add_i32 s62, s60, 4
	s_add_i32 s63, s61, 4
	s_add_i32 s64, s60, 8
	s_add_i32 s65, s61, 8
	s_add_i32 s66, s60, 12
	s_add_i32 s67, s61, 12
	s_add_i32 s68, s60, 16
	s_add_i32 s69, s61, 16
	s_add_i32 s70, s60, 20
	s_add_i32 s71, s61, 20
	s_add_i32 s72, s60, 24
	s_add_i32 s73, s61, 24
	s_add_i32 s60, s60, 28
	s_add_i32 s61, s61, 28
	v_add_u32_e32 v13, s13, v11
	v_or_b32_e32 v16, s62, v1
	v_or_b32_e32 v56, s63, v2
	v_or_b32_e32 v57, s64, v1
	v_or_b32_e32 v58, s65, v2
	v_or_b32_e32 v59, s66, v1
	v_or_b32_e32 v60, s67, v2
	v_or_b32_e32 v61, s68, v1
	v_or_b32_e32 v62, s69, v2
	v_or_b32_e32 v63, s70, v1
	v_or_b32_e32 v64, s71, v2
	v_or_b32_e32 v65, s72, v1
	v_or_b32_e32 v66, s73, v2
	v_or_b32_e32 v67, s60, v1
	v_or_b32_e32 v68, s61, v2
	v_add_u32_e32 v14, s51, v3
	v_mad_u64_u32 v[24:25], s[60:61], v13, s47, v[6:7]
	v_add_u32_e32 v13, s13, v56
	v_add_u32_e32 v28, s51, v16
	v_add_u32_e32 v34, s13, v58
	v_add_u32_e32 v32, s51, v57
	v_add_u32_e32 v38, s13, v60
	v_add_u32_e32 v36, s51, v59
	v_add_u32_e32 v42, s13, v62
	v_add_u32_e32 v40, s51, v61
	v_add_u32_e32 v46, s13, v64
	v_add_u32_e32 v44, s51, v63
	v_add_u32_e32 v50, s13, v66
	v_add_u32_e32 v48, s51, v65
	v_add_u32_e32 v54, s13, v68
	v_add_u32_e32 v52, s51, v67
	v_mad_u64_u32 v[14:15], s[60:61], v14, s47, v[6:7]
	v_mov_b32_e32 v25, v7
	v_mad_u64_u32 v[28:29], s[60:61], v28, s47, v[6:7]
	v_mad_u64_u32 v[30:31], s[60:61], v13, s47, v[6:7]
	v_mad_u64_u32 v[32:33], s[60:61], v32, s47, v[6:7]
	v_mad_u64_u32 v[34:35], s[60:61], v34, s47, v[6:7]
	v_mad_u64_u32 v[36:37], s[60:61], v36, s47, v[6:7]
	v_mad_u64_u32 v[38:39], s[60:61], v38, s47, v[6:7]
	v_mad_u64_u32 v[40:41], s[60:61], v40, s47, v[6:7]
	v_mad_u64_u32 v[42:43], s[60:61], v42, s47, v[6:7]
	v_mad_u64_u32 v[44:45], s[60:61], v44, s47, v[6:7]
	v_mad_u64_u32 v[46:47], s[60:61], v46, s47, v[6:7]
	v_mad_u64_u32 v[48:49], s[60:61], v48, s47, v[6:7]
	v_mad_u64_u32 v[50:51], s[60:61], v50, s47, v[6:7]
	v_mad_u64_u32 v[52:53], s[60:61], v52, s47, v[6:7]
	v_mad_u64_u32 v[54:55], s[60:61], v54, s47, v[6:7]
	v_mov_b32_e32 v15, v7
	v_lshl_add_u64 v[24:25], v[24:25], 2, s[8:9]
	v_mov_b32_e32 v31, v7
	v_mov_b32_e32 v29, v7
	v_mov_b32_e32 v35, v7
	v_mov_b32_e32 v33, v7
	v_mov_b32_e32 v39, v7
	v_mov_b32_e32 v37, v7
	v_mov_b32_e32 v43, v7
	v_mov_b32_e32 v41, v7
	v_mov_b32_e32 v47, v7
	v_mov_b32_e32 v45, v7
	v_mov_b32_e32 v51, v7
	v_mov_b32_e32 v49, v7
	v_mov_b32_e32 v55, v7
	v_mov_b32_e32 v53, v7
	v_lshl_add_u64 v[14:15], v[14:15], 2, s[8:9]
	v_lshl_add_u64 v[30:31], v[30:31], 2, s[8:9]
	v_lshl_add_u64 v[28:29], v[28:29], 2, s[8:9]
	v_lshl_add_u64 v[34:35], v[34:35], 2, s[8:9]
	v_lshl_add_u64 v[32:33], v[32:33], 2, s[8:9]
	v_lshl_add_u64 v[38:39], v[38:39], 2, s[8:9]
	v_lshl_add_u64 v[36:37], v[36:37], 2, s[8:9]
	v_lshl_add_u64 v[42:43], v[42:43], 2, s[8:9]
	v_lshl_add_u64 v[40:41], v[40:41], 2, s[8:9]
	v_lshl_add_u64 v[46:47], v[46:47], 2, s[8:9]
	v_lshl_add_u64 v[44:45], v[44:45], 2, s[8:9]
	v_lshl_add_u64 v[50:51], v[50:51], 2, s[8:9]
	v_lshl_add_u64 v[48:49], v[48:49], 2, s[8:9]
	v_lshl_add_u64 v[54:55], v[54:55], 2, s[8:9]
	v_lshl_add_u64 v[52:53], v[52:53], 2, s[8:9]
	global_load_dword v13, v[24:25], off
	global_load_dword v69, v[14:15], off
	global_load_dword v70, v[30:31], off
	global_load_dword v71, v[28:29], off
	global_load_dword v72, v[34:35], off
	global_load_dword v73, v[32:33], off
	global_load_dword v74, v[38:39], off
	global_load_dword v75, v[36:37], off
	global_load_dword v76, v[42:43], off
	global_load_dword v77, v[40:41], off
	global_load_dword v78, v[46:47], off
	global_load_dword v79, v[44:45], off
	global_load_dword v80, v[50:51], off
	global_load_dword v81, v[48:49], off
	global_load_dword v82, v[54:55], off
	global_load_dword v83, v[52:53], off
	s_add_i32 s12, s12, 16
	s_add_i32 s52, s52, 16
	s_add_i32 s53, s53, -16
	v_mad_u64_u32 v[14:15], s[60:61], v11, s16, v[8:9]
	v_mad_u64_u32 v[24:25], s[60:61], v3, s16, v[8:9]
	v_mad_u64_u32 v[28:29], s[60:61], v56, s16, v[8:9]
	v_mad_u64_u32 v[30:31], s[60:61], v16, s16, v[8:9]
	v_mad_u64_u32 v[32:33], s[60:61], v58, s16, v[8:9]
	v_mad_u64_u32 v[34:35], s[60:61], v57, s16, v[8:9]
	v_mad_u64_u32 v[36:37], s[60:61], v60, s16, v[8:9]
	v_mad_u64_u32 v[38:39], s[60:61], v59, s16, v[8:9]
	v_mad_u64_u32 v[40:41], s[60:61], v62, s16, v[8:9]
	v_mad_u64_u32 v[42:43], s[60:61], v61, s16, v[8:9]
	v_mad_u64_u32 v[44:45], s[60:61], v64, s16, v[8:9]
	v_mad_u64_u32 v[46:47], s[60:61], v63, s16, v[8:9]
	v_mad_u64_u32 v[48:49], s[60:61], v66, s16, v[8:9]
	v_mad_u64_u32 v[50:51], s[60:61], v65, s16, v[8:9]
	v_mad_u64_u32 v[52:53], s[60:61], v68, s16, v[8:9]
	v_mad_u64_u32 v[54:55], s[60:61], v67, s16, v[8:9]
	v_mov_b32_e32 v147, v1
	v_mov_b32_e32 v148, v2
	v_mov_b32_e32 v152, v6
	v_mov_b32_e32 v153, v7
	v_mov_b32_e32 v154, v8
	v_mov_b32_e32 v155, v9
	s_lshl_b32 s60, s52, 1
	s_lshl_b32 s61, s12, 1
	v_or_b32_e32 v149, s60, v147
	v_or_b32_e32 v157, s61, v148
	s_add_i32 s62, s60, 4
	s_add_i32 s63, s61, 4
	s_add_i32 s64, s60, 8
	s_add_i32 s65, s61, 8
	s_add_i32 s66, s60, 12
	s_add_i32 s67, s61, 12
	s_add_i32 s68, s60, 16
	s_add_i32 s69, s61, 16
	s_add_i32 s70, s60, 20
	s_add_i32 s71, s61, 20
	s_add_i32 s72, s60, 24
	s_add_i32 s73, s61, 24
	s_add_i32 s60, s60, 28
	s_add_i32 s61, s61, 28
	v_add_u32_e32 v159, s13, v157
	v_or_b32_e32 v162, s62, v147
	v_or_b32_e32 v202, s63, v148
	v_or_b32_e32 v203, s64, v147
	v_or_b32_e32 v204, s65, v148
	v_or_b32_e32 v205, s66, v147
	v_or_b32_e32 v206, s67, v148
	v_or_b32_e32 v207, s68, v147
	v_or_b32_e32 v208, s69, v148
	v_or_b32_e32 v209, s70, v147
	v_or_b32_e32 v210, s71, v148
	v_or_b32_e32 v211, s72, v147
	v_or_b32_e32 v212, s73, v148
	v_or_b32_e32 v213, s60, v147
	v_or_b32_e32 v214, s61, v148
	v_add_u32_e32 v160, s51, v149
	v_mad_u64_u32 v[170:171], s[60:61], v159, s47, v[152:153]
	v_add_u32_e32 v159, s13, v202
	v_add_u32_e32 v174, s51, v162
	v_add_u32_e32 v180, s13, v204
	v_add_u32_e32 v178, s51, v203
	v_add_u32_e32 v184, s13, v206
	v_add_u32_e32 v182, s51, v205
	v_add_u32_e32 v188, s13, v208
	v_add_u32_e32 v186, s51, v207
	v_add_u32_e32 v192, s13, v210
	v_add_u32_e32 v190, s51, v209
	v_add_u32_e32 v196, s13, v212
	v_add_u32_e32 v194, s51, v211
	v_add_u32_e32 v200, s13, v214
	v_add_u32_e32 v198, s51, v213
	v_mad_u64_u32 v[160:161], s[60:61], v160, s47, v[152:153]
	v_mov_b32_e32 v171, v153
	v_mad_u64_u32 v[174:175], s[60:61], v174, s47, v[152:153]
	v_mad_u64_u32 v[176:177], s[60:61], v159, s47, v[152:153]
	v_mad_u64_u32 v[178:179], s[60:61], v178, s47, v[152:153]
	v_mad_u64_u32 v[180:181], s[60:61], v180, s47, v[152:153]
	v_mad_u64_u32 v[182:183], s[60:61], v182, s47, v[152:153]
	v_mad_u64_u32 v[184:185], s[60:61], v184, s47, v[152:153]
	v_mad_u64_u32 v[186:187], s[60:61], v186, s47, v[152:153]
	v_mad_u64_u32 v[188:189], s[60:61], v188, s47, v[152:153]
	v_mad_u64_u32 v[190:191], s[60:61], v190, s47, v[152:153]
	v_mad_u64_u32 v[192:193], s[60:61], v192, s47, v[152:153]
	v_mad_u64_u32 v[194:195], s[60:61], v194, s47, v[152:153]
	v_mad_u64_u32 v[196:197], s[60:61], v196, s47, v[152:153]
	v_mad_u64_u32 v[198:199], s[60:61], v198, s47, v[152:153]
	v_mad_u64_u32 v[200:201], s[60:61], v200, s47, v[152:153]
	v_mov_b32_e32 v161, v153
	v_lshl_add_u64 v[170:171], v[170:171], 2, s[8:9]
	v_mov_b32_e32 v177, v153
	v_mov_b32_e32 v175, v153
	v_mov_b32_e32 v181, v153
	v_mov_b32_e32 v179, v153
	v_mov_b32_e32 v185, v153
	v_mov_b32_e32 v183, v153
	v_mov_b32_e32 v189, v153
	v_mov_b32_e32 v187, v153
	v_mov_b32_e32 v193, v153
	v_mov_b32_e32 v191, v153
	v_mov_b32_e32 v197, v153
	v_mov_b32_e32 v195, v153
	v_mov_b32_e32 v201, v153
	v_mov_b32_e32 v199, v153
	v_lshl_add_u64 v[160:161], v[160:161], 2, s[8:9]
	v_lshl_add_u64 v[176:177], v[176:177], 2, s[8:9]
	v_lshl_add_u64 v[174:175], v[174:175], 2, s[8:9]
	v_lshl_add_u64 v[180:181], v[180:181], 2, s[8:9]
	v_lshl_add_u64 v[178:179], v[178:179], 2, s[8:9]
	v_lshl_add_u64 v[184:185], v[184:185], 2, s[8:9]
	v_lshl_add_u64 v[182:183], v[182:183], 2, s[8:9]
	v_lshl_add_u64 v[188:189], v[188:189], 2, s[8:9]
	v_lshl_add_u64 v[186:187], v[186:187], 2, s[8:9]
	v_lshl_add_u64 v[192:193], v[192:193], 2, s[8:9]
	v_lshl_add_u64 v[190:191], v[190:191], 2, s[8:9]
	v_lshl_add_u64 v[196:197], v[196:197], 2, s[8:9]
	v_lshl_add_u64 v[194:195], v[194:195], 2, s[8:9]
	v_lshl_add_u64 v[200:201], v[200:201], 2, s[8:9]
	v_lshl_add_u64 v[198:199], v[198:199], 2, s[8:9]
	global_load_dword v159, v[170:171], off
	global_load_dword v215, v[160:161], off
	global_load_dword v216, v[176:177], off
	global_load_dword v217, v[174:175], off
	global_load_dword v218, v[180:181], off
	global_load_dword v219, v[178:179], off
	global_load_dword v220, v[184:185], off
	global_load_dword v221, v[182:183], off
	global_load_dword v222, v[188:189], off
	global_load_dword v223, v[186:187], off
	global_load_dword v224, v[192:193], off
	global_load_dword v225, v[190:191], off
	global_load_dword v226, v[196:197], off
	global_load_dword v227, v[194:195], off
	global_load_dword v228, v[200:201], off
	global_load_dword v229, v[198:199], off
	s_add_i32 s12, s12, 16
	s_add_i32 s52, s52, 16
	s_add_i32 s53, s53, -16
	v_mad_u64_u32 v[160:161], s[60:61], v157, s16, v[154:155]
	v_mad_u64_u32 v[170:171], s[60:61], v149, s16, v[154:155]
	v_mad_u64_u32 v[174:175], s[60:61], v202, s16, v[154:155]
	v_mad_u64_u32 v[176:177], s[60:61], v162, s16, v[154:155]
	v_mad_u64_u32 v[178:179], s[60:61], v204, s16, v[154:155]
	v_mad_u64_u32 v[180:181], s[60:61], v203, s16, v[154:155]
	v_mad_u64_u32 v[182:183], s[60:61], v206, s16, v[154:155]
	v_mad_u64_u32 v[184:185], s[60:61], v205, s16, v[154:155]
	v_mad_u64_u32 v[186:187], s[60:61], v208, s16, v[154:155]
	v_mad_u64_u32 v[188:189], s[60:61], v207, s16, v[154:155]
	v_mad_u64_u32 v[190:191], s[60:61], v210, s16, v[154:155]
	v_mad_u64_u32 v[192:193], s[60:61], v209, s16, v[154:155]
	v_mad_u64_u32 v[194:195], s[60:61], v212, s16, v[154:155]
	v_mad_u64_u32 v[196:197], s[60:61], v211, s16, v[154:155]
	v_mad_u64_u32 v[198:199], s[60:61], v214, s16, v[154:155]
	v_mad_u64_u32 v[200:201], s[60:61], v213, s16, v[154:155]
	s_waitcnt vmcnt(31)
	ds_write_b32 v14, v13
	s_waitcnt vmcnt(30)
	ds_write_b32 v24, v69
	s_waitcnt vmcnt(29)
	ds_write_b32 v28, v70
	s_waitcnt vmcnt(28)
	ds_write_b32 v30, v71
	s_waitcnt vmcnt(27)
	ds_write_b32 v32, v72
	s_waitcnt vmcnt(26)
	ds_write_b32 v34, v73
	s_waitcnt vmcnt(25)
	ds_write_b32 v36, v74
	s_waitcnt vmcnt(24)
	ds_write_b32 v38, v75
	s_waitcnt vmcnt(23)
	ds_write_b32 v40, v76
	s_waitcnt vmcnt(22)
	ds_write_b32 v42, v77
	s_waitcnt vmcnt(21)
	ds_write_b32 v44, v78
	s_waitcnt vmcnt(20)
	ds_write_b32 v46, v79
	s_waitcnt vmcnt(19)
	ds_write_b32 v48, v80
	s_waitcnt vmcnt(18)
	ds_write_b32 v50, v81
	s_waitcnt vmcnt(17)
	ds_write_b32 v52, v82
	s_waitcnt vmcnt(16)
	ds_write_b32 v54, v83
	s_waitcnt vmcnt(15)
	ds_write_b32 v160, v159
	s_waitcnt vmcnt(14)
	ds_write_b32 v170, v215
	s_waitcnt vmcnt(13)
	ds_write_b32 v174, v216
	s_waitcnt vmcnt(12)
	ds_write_b32 v176, v217
	s_waitcnt vmcnt(11)
	ds_write_b32 v178, v218
	s_waitcnt vmcnt(10)
	ds_write_b32 v180, v219
	s_waitcnt vmcnt(9)
	ds_write_b32 v182, v220
	s_waitcnt vmcnt(8)
	ds_write_b32 v184, v221
	s_waitcnt vmcnt(7)
	ds_write_b32 v186, v222
	s_waitcnt vmcnt(6)
	ds_write_b32 v188, v223
	s_waitcnt vmcnt(5)
	ds_write_b32 v190, v224
	s_waitcnt vmcnt(4)
	ds_write_b32 v192, v225
	s_waitcnt vmcnt(3)
	ds_write_b32 v194, v226
	s_waitcnt vmcnt(2)
	ds_write_b32 v196, v227
	s_waitcnt vmcnt(1)
	ds_write_b32 v198, v228
	s_waitcnt vmcnt(0)
	ds_write_b32 v200, v229
	s_lshl_b32 s8, s11, 1
	s_add_u32 s8, s21, s8
	s_addc_u32 s9, s22, 0
	s_and_b32 s11, s10, 1
	s_and_b32 s12, s6, 0x7c0
	s_or_b32 s11, s12, s11
	s_and_b32 s12, 0xffff, s13
	s_lshl_b32 s12, s12, 1
	s_add_u32 s8, s8, s12
	s_waitcnt lgkmcnt(0)
	s_addc_u32 s9, s9, 0
	ds_read2_b32 v[14:15], v23 offset0:33 offset1:41
	ds_read2_b32 v[24:25], v23 offset1:8
	ds_read2_b32 v[32:33], v23 offset0:66 offset1:74
	ds_read2_b32 v[34:35], v23 offset0:99 offset1:107
	ds_read2_b32 v[36:37], v23 offset0:132 offset1:140
	ds_read2_b32 v[38:39], v23 offset0:165 offset1:173
	ds_read2_b32 v[40:41], v23 offset0:198 offset1:206
	ds_read2_b32 v[42:43], v23 offset0:231 offset1:239
	s_cmp_lt_u32 s10, 64
	v_or_b32_e32 v3, s6, v5
	v_or_b32_e32 v6, s11, v19
	s_cselect_b64 vcc, -1, 0
	v_mov_b32_e32 v13, v7
	v_cndmask_b32_e32 v3, v3, v6, vcc
	v_lshl_add_u64 v[44:45], s[8:9], 0, v[12:13]
	v_lshlrev_b32_e32 v6, 11, v3
	v_lshl_add_u64 v[46:47], v[44:45], 0, v[6:7]
	v_or_b32_e32 v3, s6, v9
	v_or_b32_e32 v6, s11, v20
	s_waitcnt lgkmcnt(6)
	v_cvt_pk_bf16_f32 v28, v24, v14
	s_waitcnt lgkmcnt(4)
	v_cvt_pk_bf16_f32 v29, v32, v34
	s_waitcnt lgkmcnt(2)
	v_cvt_pk_bf16_f32 v30, v36, v38
	s_waitcnt lgkmcnt(0)
	v_cvt_pk_bf16_f32 v31, v40, v42
	v_cndmask_b32_e32 v3, v3, v6, vcc
	global_store_dwordx4 v[46:47], v[28:31], off
	v_lshlrev_b32_e32 v6, 11, v3
	v_or_b32_e32 v3, s6, v17
	v_cvt_pk_bf16_f32 v28, v25, v15
	v_cvt_pk_bf16_f32 v29, v33, v35
	v_cvt_pk_bf16_f32 v30, v37, v39
	v_cvt_pk_bf16_f32 v31, v41, v43
	v_lshl_add_u64 v[14:15], v[44:45], 0, v[6:7]
	ds_read2_b32 v[24:25], v23 offset0:49 offset1:57
	ds_read2_b32 v[32:33], v23 offset0:16 offset1:24
	ds_read2_b32 v[34:35], v23 offset0:82 offset1:90
	ds_read2_b32 v[36:37], v23 offset0:115 offset1:123
	ds_read2_b32 v[38:39], v23 offset0:148 offset1:156
	ds_read2_b32 v[40:41], v23 offset0:181 offset1:189
	ds_read2_b32 v[42:43], v23 offset0:214 offset1:222
	ds_read2_b32 v[46:47], v23 offset0:247 offset1:255
	v_or_b32_e32 v6, s11, v21
	v_cndmask_b32_e32 v3, v3, v6, vcc
	v_lshlrev_b32_e32 v6, 11, v3
	global_store_dwordx4 v[14:15], v[28:31], off
	v_lshl_add_u64 v[14:15], v[44:45], 0, v[6:7]
	v_or_b32_e32 v3, s6, v18
	v_or_b32_e32 v6, s11, v22
	v_cndmask_b32_e32 v3, v3, v6, vcc
	s_waitcnt lgkmcnt(6)
	v_cvt_pk_bf16_f32 v28, v32, v24
	s_waitcnt lgkmcnt(4)
	v_cvt_pk_bf16_f32 v29, v34, v36
	s_waitcnt lgkmcnt(2)
	v_cvt_pk_bf16_f32 v30, v38, v40
	s_waitcnt lgkmcnt(0)
	v_cvt_pk_bf16_f32 v31, v42, v46
	v_lshlrev_b32_e32 v6, 11, v3
	global_store_dwordx4 v[14:15], v[28:31], off
	v_lshl_add_u64 v[14:15], v[44:45], 0, v[6:7]
	s_nop 0
	v_cvt_pk_bf16_f32 v28, v33, v25
	v_cvt_pk_bf16_f32 v29, v35, v37
	v_cvt_pk_bf16_f32 v30, v39, v41
	v_cvt_pk_bf16_f32 v31, v43, v47
	global_store_dwordx4 v[14:15], v[28:31], off
	s_waitcnt lgkmcnt(0)

.LBB0_45:
	s_lshl_b32 s51, s11, 1
	s_lshl_b32 s52, s12, 1
	v_or_b32_e32 v6, s52, v16
	s_add_i32 s60, s51, 4
	s_add_i32 s61, s52, 4
	v_mov_b32_e32 v29, v7
	s_add_i32 s63, s52, 8
	v_lshlrev_b64 v[42:43], 11, v[6:7]
	v_or_b32_e32 v28, s60, v3
	v_or_b32_e32 v6, s61, v16
	v_mov_b32_e32 v25, v7
	v_or_b32_e32 v24, s51, v3
	s_add_i32 s65, s52, 12
	v_lshlrev_b64 v[28:29], 11, v[28:29]
	v_lshlrev_b64 v[44:45], 11, v[6:7]
	v_or_b32_e32 v6, s63, v16
	s_add_i32 s62, s51, 8
	s_add_i32 s64, s51, 12
	s_add_i32 s67, s52, 16
	v_lshlrev_b64 v[24:25], 11, v[24:25]
	v_lshl_add_u64 v[42:43], v[14:15], 0, v[42:43]
	v_lshl_add_u64 v[28:29], v[14:15], 0, v[28:29]
	v_lshlrev_b64 v[46:47], 11, v[6:7]
	v_or_b32_e32 v6, s65, v16
	v_mov_b32_e32 v31, v7
	v_mov_b32_e32 v33, v7
	s_add_i32 s69, s52, 20
	v_or_b32_e32 v30, s62, v3
	v_or_b32_e32 v32, s64, v3
	v_lshl_add_u64 v[24:25], v[14:15], 0, v[24:25]
	v_lshl_add_u64 v[44:45], v[14:15], 0, v[44:45]
	global_load_dword v11, v[42:43], off
	global_load_dword v13, v[24:25], off
	global_load_dword v58, v[44:45], off
	global_load_dword v59, v[28:29], off
	v_lshlrev_b64 v[28:29], 11, v[6:7]
	v_or_b32_e32 v6, s67, v16
	s_add_i32 s66, s51, 16
	s_add_i32 s68, s51, 20
	s_add_i32 s71, s52, 24
	v_lshlrev_b64 v[30:31], 11, v[30:31]
	v_lshlrev_b64 v[32:33], 11, v[32:33]
	v_lshl_add_u64 v[24:25], v[14:15], 0, v[46:47]
	v_lshl_add_u64 v[28:29], v[14:15], 0, v[28:29]
	v_lshlrev_b64 v[42:43], 11, v[6:7]
	v_or_b32_e32 v6, s69, v16
	v_mov_b32_e32 v35, v7
	v_mov_b32_e32 v37, v7
	s_add_i32 s70, s51, 24
	s_add_i32 s72, s51, 28
	s_add_i32 s73, s52, 28
	v_or_b32_e32 v34, s66, v3
	v_or_b32_e32 v36, s68, v3
	v_lshl_add_u64 v[30:31], v[14:15], 0, v[30:31]
	v_lshl_add_u64 v[32:33], v[14:15], 0, v[32:33]
	global_load_dword v60, v[24:25], off
	global_load_dword v61, v[30:31], off
	global_load_dword v62, v[28:29], off
	global_load_dword v63, v[32:33], off
	v_lshlrev_b64 v[28:29], 11, v[6:7]
	v_or_b32_e32 v6, s71, v16
	v_mov_b32_e32 v39, v7
	v_mov_b32_e32 v41, v7
	v_or_b32_e32 v38, s70, v3
	v_or_b32_e32 v40, s72, v3
	v_lshlrev_b64 v[34:35], 11, v[34:35]
	v_lshlrev_b64 v[36:37], 11, v[36:37]
	v_lshl_add_u64 v[24:25], v[14:15], 0, v[42:43]
	v_lshl_add_u64 v[28:29], v[14:15], 0, v[28:29]
	v_lshlrev_b64 v[30:31], 11, v[6:7]
	v_or_b32_e32 v6, s73, v16
	v_lshlrev_b64 v[38:39], 11, v[38:39]
	v_lshlrev_b64 v[40:41], 11, v[40:41]
	v_lshl_add_u64 v[34:35], v[14:15], 0, v[34:35]
	v_lshl_add_u64 v[36:37], v[14:15], 0, v[36:37]
	global_load_dword v64, v[24:25], off
	global_load_dword v65, v[34:35], off
	global_load_dword v66, v[28:29], off
	global_load_dword v67, v[36:37], off
	v_lshl_add_u64 v[24:25], v[14:15], 0, v[30:31]
	v_lshlrev_b64 v[28:29], 11, v[6:7]
	v_lshl_add_u64 v[38:39], v[14:15], 0, v[38:39]
	v_lshl_add_u64 v[40:41], v[14:15], 0, v[40:41]
	v_lshl_add_u64 v[28:29], v[14:15], 0, v[28:29]
	global_load_dword v6, v[24:25], off
	global_load_dword v68, v[38:39], off
	global_load_dword v69, v[28:29], off
	global_load_dword v70, v[40:41], off
	v_or_b32_e32 v28, s51, v1
	v_or_b32_e32 v24, s52, v2
	s_add_i32 s12, s12, 16
	s_add_i32 s11, s11, 16
	s_add_i32 s13, s13, -16
	v_mad_u64_u32 v[24:25], s[52:53], v24, s16, v[8:9]
	v_mad_u64_u32 v[28:29], s[52:53], v28, s16, v[8:9]
	v_or_b32_e32 v25, s60, v1
	v_or_b32_e32 v29, s61, v2
	v_or_b32_e32 v36, s62, v1
	v_or_b32_e32 v34, s63, v2
	v_or_b32_e32 v40, s64, v1
	v_or_b32_e32 v38, s65, v2
	v_or_b32_e32 v44, s66, v1
	v_or_b32_e32 v42, s67, v2
	v_or_b32_e32 v48, s68, v1
	v_or_b32_e32 v46, s69, v2
	v_or_b32_e32 v52, s70, v1
	v_or_b32_e32 v50, s71, v2
	v_or_b32_e32 v56, s72, v1
	v_or_b32_e32 v54, s73, v2
	v_mad_u64_u32 v[30:31], s[52:53], v29, s16, v[8:9]
	v_mad_u64_u32 v[32:33], s[52:53], v25, s16, v[8:9]
	v_mad_u64_u32 v[34:35], s[52:53], v34, s16, v[8:9]
	v_mad_u64_u32 v[36:37], s[52:53], v36, s16, v[8:9]
	v_mad_u64_u32 v[38:39], s[52:53], v38, s16, v[8:9]
	v_mad_u64_u32 v[40:41], s[52:53], v40, s16, v[8:9]
	v_mad_u64_u32 v[42:43], s[52:53], v42, s16, v[8:9]
	v_mad_u64_u32 v[44:45], s[52:53], v44, s16, v[8:9]
	v_mad_u64_u32 v[46:47], s[52:53], v46, s16, v[8:9]
	v_mad_u64_u32 v[48:49], s[52:53], v48, s16, v[8:9]
	v_mad_u64_u32 v[50:51], s[52:53], v50, s16, v[8:9]
	v_mad_u64_u32 v[52:53], s[52:53], v52, s16, v[8:9]
	v_mad_u64_u32 v[54:55], s[52:53], v54, s16, v[8:9]
	v_mad_u64_u32 v[56:57], s[52:53], v56, s16, v[8:9]
	v_mov_b32_e32 v147, v1
	v_mov_b32_e32 v148, v2
	v_mov_b32_e32 v149, v3
	v_mov_b32_e32 v153, v7
	v_mov_b32_e32 v154, v8
	v_mov_b32_e32 v155, v9
	v_mov_b32_e32 v160, v14
	v_mov_b32_e32 v161, v15
	v_mov_b32_e32 v162, v16
	s_lshl_b32 s51, s11, 1
	s_lshl_b32 s52, s12, 1
	v_or_b32_e32 v152, s52, v162
	s_add_i32 s60, s51, 4
	s_add_i32 s61, s52, 4
	v_mov_b32_e32 v175, v153
	s_add_i32 s63, s52, 8
	v_lshlrev_b64 v[188:189], 11, v[152:153]
	v_or_b32_e32 v174, s60, v149
	v_or_b32_e32 v152, s61, v162
	v_mov_b32_e32 v171, v153
	v_or_b32_e32 v170, s51, v149
	s_add_i32 s65, s52, 12
	v_lshlrev_b64 v[174:175], 11, v[174:175]
	v_lshlrev_b64 v[190:191], 11, v[152:153]
	v_or_b32_e32 v152, s63, v162
	s_add_i32 s62, s51, 8
	s_add_i32 s64, s51, 12
	s_add_i32 s67, s52, 16
	v_lshlrev_b64 v[170:171], 11, v[170:171]
	v_lshl_add_u64 v[188:189], v[160:161], 0, v[188:189]
	v_lshl_add_u64 v[174:175], v[160:161], 0, v[174:175]
	v_lshlrev_b64 v[192:193], 11, v[152:153]
	v_or_b32_e32 v152, s65, v162
	v_mov_b32_e32 v177, v153
	v_mov_b32_e32 v179, v153
	s_add_i32 s69, s52, 20
	v_or_b32_e32 v176, s62, v149
	v_or_b32_e32 v178, s64, v149
	v_lshl_add_u64 v[170:171], v[160:161], 0, v[170:171]
	v_lshl_add_u64 v[190:191], v[160:161], 0, v[190:191]
	global_load_dword v157, v[188:189], off
	global_load_dword v159, v[170:171], off
	global_load_dword v204, v[190:191], off
	global_load_dword v205, v[174:175], off
	v_lshlrev_b64 v[174:175], 11, v[152:153]
	v_or_b32_e32 v152, s67, v162
	s_add_i32 s66, s51, 16
	s_add_i32 s68, s51, 20
	s_add_i32 s71, s52, 24
	v_lshlrev_b64 v[176:177], 11, v[176:177]
	v_lshlrev_b64 v[178:179], 11, v[178:179]
	v_lshl_add_u64 v[170:171], v[160:161], 0, v[192:193]
	v_lshl_add_u64 v[174:175], v[160:161], 0, v[174:175]
	v_lshlrev_b64 v[188:189], 11, v[152:153]
	v_or_b32_e32 v152, s69, v162
	v_mov_b32_e32 v181, v153
	v_mov_b32_e32 v183, v153
	s_add_i32 s70, s51, 24
	s_add_i32 s72, s51, 28
	s_add_i32 s73, s52, 28
	v_or_b32_e32 v180, s66, v149
	v_or_b32_e32 v182, s68, v149
	v_lshl_add_u64 v[176:177], v[160:161], 0, v[176:177]
	v_lshl_add_u64 v[178:179], v[160:161], 0, v[178:179]
	global_load_dword v206, v[170:171], off
	global_load_dword v207, v[176:177], off
	global_load_dword v208, v[174:175], off
	global_load_dword v209, v[178:179], off
	v_lshlrev_b64 v[174:175], 11, v[152:153]
	v_or_b32_e32 v152, s71, v162
	v_mov_b32_e32 v185, v153
	v_mov_b32_e32 v187, v153
	v_or_b32_e32 v184, s70, v149
	v_or_b32_e32 v186, s72, v149
	v_lshlrev_b64 v[180:181], 11, v[180:181]
	v_lshlrev_b64 v[182:183], 11, v[182:183]
	v_lshl_add_u64 v[170:171], v[160:161], 0, v[188:189]
	v_lshl_add_u64 v[174:175], v[160:161], 0, v[174:175]
	v_lshlrev_b64 v[176:177], 11, v[152:153]
	v_or_b32_e32 v152, s73, v162
	v_lshlrev_b64 v[184:185], 11, v[184:185]
	v_lshlrev_b64 v[186:187], 11, v[186:187]
	v_lshl_add_u64 v[180:181], v[160:161], 0, v[180:181]
	v_lshl_add_u64 v[182:183], v[160:161], 0, v[182:183]
	global_load_dword v210, v[170:171], off
	global_load_dword v211, v[180:181], off
	global_load_dword v212, v[174:175], off
	global_load_dword v213, v[182:183], off
	v_lshl_add_u64 v[170:171], v[160:161], 0, v[176:177]
	v_lshlrev_b64 v[174:175], 11, v[152:153]
	v_lshl_add_u64 v[184:185], v[160:161], 0, v[184:185]
	v_lshl_add_u64 v[186:187], v[160:161], 0, v[186:187]
	v_lshl_add_u64 v[174:175], v[160:161], 0, v[174:175]
	global_load_dword v152, v[170:171], off
	global_load_dword v214, v[184:185], off
	global_load_dword v215, v[174:175], off
	global_load_dword v216, v[186:187], off
	v_or_b32_e32 v174, s51, v147
	v_or_b32_e32 v170, s52, v148
	s_add_i32 s12, s12, 16
	s_add_i32 s11, s11, 16
	s_add_i32 s13, s13, -16
	v_mad_u64_u32 v[170:171], s[52:53], v170, s16, v[154:155]
	v_mad_u64_u32 v[174:175], s[52:53], v174, s16, v[154:155]
	v_or_b32_e32 v171, s60, v147
	v_or_b32_e32 v175, s61, v148
	v_or_b32_e32 v182, s62, v147
	v_or_b32_e32 v180, s63, v148
	v_or_b32_e32 v186, s64, v147
	v_or_b32_e32 v184, s65, v148
	v_or_b32_e32 v190, s66, v147
	v_or_b32_e32 v188, s67, v148
	v_or_b32_e32 v194, s68, v147
	v_or_b32_e32 v192, s69, v148
	v_or_b32_e32 v198, s70, v147
	v_or_b32_e32 v196, s71, v148
	v_or_b32_e32 v202, s72, v147
	v_or_b32_e32 v200, s73, v148
	v_mad_u64_u32 v[176:177], s[52:53], v175, s16, v[154:155]
	v_mad_u64_u32 v[178:179], s[52:53], v171, s16, v[154:155]
	v_mad_u64_u32 v[180:181], s[52:53], v180, s16, v[154:155]
	v_mad_u64_u32 v[182:183], s[52:53], v182, s16, v[154:155]
	v_mad_u64_u32 v[184:185], s[52:53], v184, s16, v[154:155]
	v_mad_u64_u32 v[186:187], s[52:53], v186, s16, v[154:155]
	v_mad_u64_u32 v[188:189], s[52:53], v188, s16, v[154:155]
	v_mad_u64_u32 v[190:191], s[52:53], v190, s16, v[154:155]
	v_mad_u64_u32 v[192:193], s[52:53], v192, s16, v[154:155]
	v_mad_u64_u32 v[194:195], s[52:53], v194, s16, v[154:155]
	v_mad_u64_u32 v[196:197], s[52:53], v196, s16, v[154:155]
	v_mad_u64_u32 v[198:199], s[52:53], v198, s16, v[154:155]
	v_mad_u64_u32 v[200:201], s[52:53], v200, s16, v[154:155]
	v_mad_u64_u32 v[202:203], s[52:53], v202, s16, v[154:155]
	s_waitcnt vmcnt(31)
	ds_write_b32 v24, v11
	s_waitcnt vmcnt(30)
	ds_write_b32 v28, v13
	s_waitcnt vmcnt(29)
	ds_write_b32 v30, v58
	s_waitcnt vmcnt(28)
	ds_write_b32 v32, v59
	s_waitcnt vmcnt(27)
	ds_write_b32 v34, v60
	s_waitcnt vmcnt(26)
	ds_write_b32 v36, v61
	s_waitcnt vmcnt(25)
	ds_write_b32 v38, v62
	s_waitcnt vmcnt(24)
	ds_write_b32 v40, v63
	s_waitcnt vmcnt(23)
	ds_write_b32 v42, v64
	s_waitcnt vmcnt(22)
	ds_write_b32 v44, v65
	s_waitcnt vmcnt(21)
	ds_write_b32 v46, v66
	s_waitcnt vmcnt(20)
	ds_write_b32 v48, v67
	s_waitcnt vmcnt(19)
	ds_write_b32 v50, v6
	s_waitcnt vmcnt(18)
	ds_write_b32 v52, v68
	s_waitcnt vmcnt(17)
	ds_write_b32 v54, v69
	s_waitcnt vmcnt(16)
	ds_write_b32 v56, v70
	s_waitcnt vmcnt(15)
	ds_write_b32 v170, v157
	s_waitcnt vmcnt(14)
	ds_write_b32 v174, v159
	s_waitcnt vmcnt(13)
	ds_write_b32 v176, v204
	s_waitcnt vmcnt(12)
	ds_write_b32 v178, v205
	s_waitcnt vmcnt(11)
	ds_write_b32 v180, v206
	s_waitcnt vmcnt(10)
	ds_write_b32 v182, v207
	s_waitcnt vmcnt(9)
	ds_write_b32 v184, v208
	s_waitcnt vmcnt(8)
	ds_write_b32 v186, v209
	s_waitcnt vmcnt(7)
	ds_write_b32 v188, v210
	s_waitcnt vmcnt(6)
	ds_write_b32 v190, v211
	s_waitcnt vmcnt(5)
	ds_write_b32 v192, v212
	s_waitcnt vmcnt(4)
	ds_write_b32 v194, v213
	s_waitcnt vmcnt(3)
	ds_write_b32 v196, v152
	s_waitcnt vmcnt(2)
	ds_write_b32 v198, v214
	s_waitcnt vmcnt(1)
	ds_write_b32 v200, v215
	s_waitcnt vmcnt(0)
	ds_write_b32 v202, v216
	s_lshl_b64 s[8:9], s[8:9], 1
	s_waitcnt lgkmcnt(0)
	s_add_u32 s8, s23, s8
	ds_read2_b32 v[14:15], v23 offset0:33 offset1:41
	ds_read2_b32 v[24:25], v23 offset1:8
	ds_read2_b32 v[32:33], v23 offset0:66 offset1:74
	ds_read2_b32 v[34:35], v23 offset0:99 offset1:107
	ds_read2_b32 v[36:37], v23 offset0:132 offset1:140
	ds_read2_b32 v[38:39], v23 offset0:165 offset1:173
	ds_read2_b32 v[40:41], v23 offset0:198 offset1:206
	ds_read2_b32 v[42:43], v23 offset0:231 offset1:239
	s_addc_u32 s9, s34, s9
	s_lshl_b32 s10, s10, 1
	s_add_u32 s8, s8, s10
	s_addc_u32 s9, s9, 0
	v_mov_b32_e32 v13, v7
	v_or_b32_e32 v3, s6, v5
	v_lshl_add_u64 v[44:45], s[8:9], 0, v[12:13]
	v_lshlrev_b32_e32 v6, 10, v3
	s_waitcnt lgkmcnt(6)
	v_cvt_pk_bf16_f32 v28, v24, v14
	s_waitcnt lgkmcnt(4)
	v_cvt_pk_bf16_f32 v29, v32, v34
	s_waitcnt lgkmcnt(2)
	v_cvt_pk_bf16_f32 v30, v36, v38
	s_waitcnt lgkmcnt(0)
	v_cvt_pk_bf16_f32 v31, v40, v42
	v_lshl_add_u64 v[46:47], v[44:45], 0, v[6:7]
	global_store_dwordx4 v[46:47], v[28:31], off
	v_or_b32_e32 v3, s6, v9
	v_lshlrev_b32_e32 v6, 10, v3
	v_cvt_pk_bf16_f32 v28, v25, v15
	v_cvt_pk_bf16_f32 v29, v33, v35
	v_cvt_pk_bf16_f32 v30, v37, v39
	v_cvt_pk_bf16_f32 v31, v41, v43
	ds_read2_b32 v[24:25], v23 offset0:49 offset1:57
	ds_read2_b32 v[32:33], v23 offset0:16 offset1:24
	ds_read2_b32 v[34:35], v23 offset0:82 offset1:90
	ds_read2_b32 v[36:37], v23 offset0:115 offset1:123
	ds_read2_b32 v[38:39], v23 offset0:148 offset1:156
	ds_read2_b32 v[40:41], v23 offset0:181 offset1:189
	ds_read2_b32 v[42:43], v23 offset0:214 offset1:222
	ds_read2_b32 v[46:47], v23 offset0:247 offset1:255
	v_or_b32_e32 v3, s6, v17
	v_lshl_add_u64 v[14:15], v[44:45], 0, v[6:7]
	v_lshlrev_b32_e32 v6, 10, v3
	v_or_b32_e32 v3, s6, v18
	global_store_dwordx4 v[14:15], v[28:31], off
	v_lshl_add_u64 v[14:15], v[44:45], 0, v[6:7]
	v_lshlrev_b32_e32 v6, 10, v3
	s_waitcnt lgkmcnt(6)
	v_cvt_pk_bf16_f32 v28, v32, v24
	s_waitcnt lgkmcnt(4)
	v_cvt_pk_bf16_f32 v29, v34, v36
	s_waitcnt lgkmcnt(2)
	v_cvt_pk_bf16_f32 v30, v38, v40
	s_waitcnt lgkmcnt(0)
	v_cvt_pk_bf16_f32 v31, v42, v46
	global_store_dwordx4 v[14:15], v[28:31], off
	v_lshl_add_u64 v[14:15], v[44:45], 0, v[6:7]
	s_nop 0
	v_cvt_pk_bf16_f32 v28, v33, v25
	v_cvt_pk_bf16_f32 v29, v35, v37
	v_cvt_pk_bf16_f32 v30, v39, v41
	v_cvt_pk_bf16_f32 v31, v43, v47
	global_store_dwordx4 v[14:15], v[28:31], off
	s_waitcnt lgkmcnt(0)

.LBB0_50:
	s_lshl_b32 s51, s11, 1
	s_lshl_b32 s52, s12, 1
	v_or_b32_e32 v6, s52, v16
	s_add_i32 s60, s51, 4
	s_add_i32 s61, s52, 4
	v_mov_b32_e32 v29, v7
	s_add_i32 s63, s52, 8
	v_lshlrev_b64 v[42:43], 12, v[6:7]
	v_or_b32_e32 v28, s60, v3
	v_or_b32_e32 v6, s61, v16
	v_mov_b32_e32 v25, v7
	v_or_b32_e32 v24, s51, v3
	s_add_i32 s65, s52, 12
	v_lshlrev_b64 v[28:29], 12, v[28:29]
	v_lshlrev_b64 v[44:45], 12, v[6:7]
	v_or_b32_e32 v6, s63, v16
	s_add_i32 s62, s51, 8
	s_add_i32 s64, s51, 12
	s_add_i32 s67, s52, 16
	v_lshlrev_b64 v[24:25], 12, v[24:25]
	v_lshl_add_u64 v[42:43], v[14:15], 0, v[42:43]
	v_lshl_add_u64 v[28:29], v[14:15], 0, v[28:29]
	v_lshlrev_b64 v[46:47], 12, v[6:7]
	v_or_b32_e32 v6, s65, v16
	v_mov_b32_e32 v31, v7
	v_mov_b32_e32 v33, v7
	s_add_i32 s69, s52, 20
	v_or_b32_e32 v30, s62, v3
	v_or_b32_e32 v32, s64, v3
	v_lshl_add_u64 v[24:25], v[14:15], 0, v[24:25]
	v_lshl_add_u64 v[44:45], v[14:15], 0, v[44:45]
	global_load_dword v11, v[42:43], off
	global_load_dword v13, v[24:25], off
	global_load_dword v58, v[44:45], off
	global_load_dword v59, v[28:29], off
	v_lshlrev_b64 v[28:29], 12, v[6:7]
	v_or_b32_e32 v6, s67, v16
	s_add_i32 s66, s51, 16
	s_add_i32 s68, s51, 20
	s_add_i32 s71, s52, 24
	v_lshlrev_b64 v[30:31], 12, v[30:31]
	v_lshlrev_b64 v[32:33], 12, v[32:33]
	v_lshl_add_u64 v[24:25], v[14:15], 0, v[46:47]
	v_lshl_add_u64 v[28:29], v[14:15], 0, v[28:29]
	v_lshlrev_b64 v[42:43], 12, v[6:7]
	v_or_b32_e32 v6, s69, v16
	v_mov_b32_e32 v35, v7
	v_mov_b32_e32 v37, v7
	s_add_i32 s70, s51, 24
	s_add_i32 s72, s51, 28
	s_add_i32 s73, s52, 28
	v_or_b32_e32 v34, s66, v3
	v_or_b32_e32 v36, s68, v3
	v_lshl_add_u64 v[30:31], v[14:15], 0, v[30:31]
	v_lshl_add_u64 v[32:33], v[14:15], 0, v[32:33]
	global_load_dword v60, v[24:25], off
	global_load_dword v61, v[30:31], off
	global_load_dword v62, v[28:29], off
	global_load_dword v63, v[32:33], off
	v_lshlrev_b64 v[28:29], 12, v[6:7]
	v_or_b32_e32 v6, s71, v16
	v_mov_b32_e32 v39, v7
	v_mov_b32_e32 v41, v7
	v_or_b32_e32 v38, s70, v3
	v_or_b32_e32 v40, s72, v3
	v_lshlrev_b64 v[34:35], 12, v[34:35]
	v_lshlrev_b64 v[36:37], 12, v[36:37]
	v_lshl_add_u64 v[24:25], v[14:15], 0, v[42:43]
	v_lshl_add_u64 v[28:29], v[14:15], 0, v[28:29]
	v_lshlrev_b64 v[30:31], 12, v[6:7]
	v_or_b32_e32 v6, s73, v16
	v_lshlrev_b64 v[38:39], 12, v[38:39]
	v_lshlrev_b64 v[40:41], 12, v[40:41]
	v_lshl_add_u64 v[34:35], v[14:15], 0, v[34:35]
	v_lshl_add_u64 v[36:37], v[14:15], 0, v[36:37]
	global_load_dword v64, v[24:25], off
	global_load_dword v65, v[34:35], off
	global_load_dword v66, v[28:29], off
	global_load_dword v67, v[36:37], off
	v_lshl_add_u64 v[24:25], v[14:15], 0, v[30:31]
	v_lshlrev_b64 v[28:29], 12, v[6:7]
	v_lshl_add_u64 v[38:39], v[14:15], 0, v[38:39]
	v_lshl_add_u64 v[40:41], v[14:15], 0, v[40:41]
	v_lshl_add_u64 v[28:29], v[14:15], 0, v[28:29]
	global_load_dword v6, v[24:25], off
	global_load_dword v68, v[38:39], off
	global_load_dword v69, v[28:29], off
	global_load_dword v70, v[40:41], off
	v_or_b32_e32 v28, s51, v1
	v_or_b32_e32 v24, s52, v2
	s_add_i32 s12, s12, 16
	s_add_i32 s11, s11, 16
	s_add_i32 s13, s13, -16
	v_mad_u64_u32 v[24:25], s[52:53], v24, s16, v[8:9]
	v_mad_u64_u32 v[28:29], s[52:53], v28, s16, v[8:9]
	v_or_b32_e32 v25, s60, v1
	v_or_b32_e32 v29, s61, v2
	v_or_b32_e32 v36, s62, v1
	v_or_b32_e32 v34, s63, v2
	v_or_b32_e32 v40, s64, v1
	v_or_b32_e32 v38, s65, v2
	v_or_b32_e32 v44, s66, v1
	v_or_b32_e32 v42, s67, v2
	v_or_b32_e32 v48, s68, v1
	v_or_b32_e32 v46, s69, v2
	v_or_b32_e32 v52, s70, v1
	v_or_b32_e32 v50, s71, v2
	v_or_b32_e32 v56, s72, v1
	v_or_b32_e32 v54, s73, v2
	v_mad_u64_u32 v[30:31], s[52:53], v29, s16, v[8:9]
	v_mad_u64_u32 v[32:33], s[52:53], v25, s16, v[8:9]
	v_mad_u64_u32 v[34:35], s[52:53], v34, s16, v[8:9]
	v_mad_u64_u32 v[36:37], s[52:53], v36, s16, v[8:9]
	v_mad_u64_u32 v[38:39], s[52:53], v38, s16, v[8:9]
	v_mad_u64_u32 v[40:41], s[52:53], v40, s16, v[8:9]
	v_mad_u64_u32 v[42:43], s[52:53], v42, s16, v[8:9]
	v_mad_u64_u32 v[44:45], s[52:53], v44, s16, v[8:9]
	v_mad_u64_u32 v[46:47], s[52:53], v46, s16, v[8:9]
	v_mad_u64_u32 v[48:49], s[52:53], v48, s16, v[8:9]
	v_mad_u64_u32 v[50:51], s[52:53], v50, s16, v[8:9]
	v_mad_u64_u32 v[52:53], s[52:53], v52, s16, v[8:9]
	v_mad_u64_u32 v[54:55], s[52:53], v54, s16, v[8:9]
	v_mad_u64_u32 v[56:57], s[52:53], v56, s16, v[8:9]
	v_mov_b32_e32 v147, v1
	v_mov_b32_e32 v148, v2
	v_mov_b32_e32 v149, v3
	v_mov_b32_e32 v153, v7
	v_mov_b32_e32 v154, v8
	v_mov_b32_e32 v155, v9
	v_mov_b32_e32 v160, v14
	v_mov_b32_e32 v161, v15
	v_mov_b32_e32 v162, v16
	s_lshl_b32 s51, s11, 1
	s_lshl_b32 s52, s12, 1
	v_or_b32_e32 v152, s52, v162
	s_add_i32 s60, s51, 4
	s_add_i32 s61, s52, 4
	v_mov_b32_e32 v175, v153
	s_add_i32 s63, s52, 8
	v_lshlrev_b64 v[188:189], 12, v[152:153]
	v_or_b32_e32 v174, s60, v149
	v_or_b32_e32 v152, s61, v162
	v_mov_b32_e32 v171, v153
	v_or_b32_e32 v170, s51, v149
	s_add_i32 s65, s52, 12
	v_lshlrev_b64 v[174:175], 12, v[174:175]
	v_lshlrev_b64 v[190:191], 12, v[152:153]
	v_or_b32_e32 v152, s63, v162
	s_add_i32 s62, s51, 8
	s_add_i32 s64, s51, 12
	s_add_i32 s67, s52, 16
	v_lshlrev_b64 v[170:171], 12, v[170:171]
	v_lshl_add_u64 v[188:189], v[160:161], 0, v[188:189]
	v_lshl_add_u64 v[174:175], v[160:161], 0, v[174:175]
	v_lshlrev_b64 v[192:193], 12, v[152:153]
	v_or_b32_e32 v152, s65, v162
	v_mov_b32_e32 v177, v153
	v_mov_b32_e32 v179, v153
	s_add_i32 s69, s52, 20
	v_or_b32_e32 v176, s62, v149
	v_or_b32_e32 v178, s64, v149
	v_lshl_add_u64 v[170:171], v[160:161], 0, v[170:171]
	v_lshl_add_u64 v[190:191], v[160:161], 0, v[190:191]
	global_load_dword v157, v[188:189], off
	global_load_dword v159, v[170:171], off
	global_load_dword v204, v[190:191], off
	global_load_dword v205, v[174:175], off
	v_lshlrev_b64 v[174:175], 12, v[152:153]
	v_or_b32_e32 v152, s67, v162
	s_add_i32 s66, s51, 16
	s_add_i32 s68, s51, 20
	s_add_i32 s71, s52, 24
	v_lshlrev_b64 v[176:177], 12, v[176:177]
	v_lshlrev_b64 v[178:179], 12, v[178:179]
	v_lshl_add_u64 v[170:171], v[160:161], 0, v[192:193]
	v_lshl_add_u64 v[174:175], v[160:161], 0, v[174:175]
	v_lshlrev_b64 v[188:189], 12, v[152:153]
	v_or_b32_e32 v152, s69, v162
	v_mov_b32_e32 v181, v153
	v_mov_b32_e32 v183, v153
	s_add_i32 s70, s51, 24
	s_add_i32 s72, s51, 28
	s_add_i32 s73, s52, 28
	v_or_b32_e32 v180, s66, v149
	v_or_b32_e32 v182, s68, v149
	v_lshl_add_u64 v[176:177], v[160:161], 0, v[176:177]
	v_lshl_add_u64 v[178:179], v[160:161], 0, v[178:179]
	global_load_dword v206, v[170:171], off
	global_load_dword v207, v[176:177], off
	global_load_dword v208, v[174:175], off
	global_load_dword v209, v[178:179], off
	v_lshlrev_b64 v[174:175], 12, v[152:153]
	v_or_b32_e32 v152, s71, v162
	v_mov_b32_e32 v185, v153
	v_mov_b32_e32 v187, v153
	v_or_b32_e32 v184, s70, v149
	v_or_b32_e32 v186, s72, v149
	v_lshlrev_b64 v[180:181], 12, v[180:181]
	v_lshlrev_b64 v[182:183], 12, v[182:183]
	v_lshl_add_u64 v[170:171], v[160:161], 0, v[188:189]
	v_lshl_add_u64 v[174:175], v[160:161], 0, v[174:175]
	v_lshlrev_b64 v[176:177], 12, v[152:153]
	v_or_b32_e32 v152, s73, v162
	v_lshlrev_b64 v[184:185], 12, v[184:185]
	v_lshlrev_b64 v[186:187], 12, v[186:187]
	v_lshl_add_u64 v[180:181], v[160:161], 0, v[180:181]
	v_lshl_add_u64 v[182:183], v[160:161], 0, v[182:183]
	global_load_dword v210, v[170:171], off
	global_load_dword v211, v[180:181], off
	global_load_dword v212, v[174:175], off
	global_load_dword v213, v[182:183], off
	v_lshl_add_u64 v[170:171], v[160:161], 0, v[176:177]
	v_lshlrev_b64 v[174:175], 12, v[152:153]
	v_lshl_add_u64 v[184:185], v[160:161], 0, v[184:185]
	v_lshl_add_u64 v[186:187], v[160:161], 0, v[186:187]
	v_lshl_add_u64 v[174:175], v[160:161], 0, v[174:175]
	global_load_dword v152, v[170:171], off
	global_load_dword v214, v[184:185], off
	global_load_dword v215, v[174:175], off
	global_load_dword v216, v[186:187], off
	v_or_b32_e32 v174, s51, v147
	v_or_b32_e32 v170, s52, v148
	s_add_i32 s12, s12, 16
	s_add_i32 s11, s11, 16
	s_add_i32 s13, s13, -16
	v_mad_u64_u32 v[170:171], s[52:53], v170, s16, v[154:155]
	v_mad_u64_u32 v[174:175], s[52:53], v174, s16, v[154:155]
	v_or_b32_e32 v171, s60, v147
	v_or_b32_e32 v175, s61, v148
	v_or_b32_e32 v182, s62, v147
	v_or_b32_e32 v180, s63, v148
	v_or_b32_e32 v186, s64, v147
	v_or_b32_e32 v184, s65, v148
	v_or_b32_e32 v190, s66, v147
	v_or_b32_e32 v188, s67, v148
	v_or_b32_e32 v194, s68, v147
	v_or_b32_e32 v192, s69, v148
	v_or_b32_e32 v198, s70, v147
	v_or_b32_e32 v196, s71, v148
	v_or_b32_e32 v202, s72, v147
	v_or_b32_e32 v200, s73, v148
	v_mad_u64_u32 v[176:177], s[52:53], v175, s16, v[154:155]
	v_mad_u64_u32 v[178:179], s[52:53], v171, s16, v[154:155]
	v_mad_u64_u32 v[180:181], s[52:53], v180, s16, v[154:155]
	v_mad_u64_u32 v[182:183], s[52:53], v182, s16, v[154:155]
	v_mad_u64_u32 v[184:185], s[52:53], v184, s16, v[154:155]
	v_mad_u64_u32 v[186:187], s[52:53], v186, s16, v[154:155]
	v_mad_u64_u32 v[188:189], s[52:53], v188, s16, v[154:155]
	v_mad_u64_u32 v[190:191], s[52:53], v190, s16, v[154:155]
	v_mad_u64_u32 v[192:193], s[52:53], v192, s16, v[154:155]
	v_mad_u64_u32 v[194:195], s[52:53], v194, s16, v[154:155]
	v_mad_u64_u32 v[196:197], s[52:53], v196, s16, v[154:155]
	v_mad_u64_u32 v[198:199], s[52:53], v198, s16, v[154:155]
	v_mad_u64_u32 v[200:201], s[52:53], v200, s16, v[154:155]
	v_mad_u64_u32 v[202:203], s[52:53], v202, s16, v[154:155]
	s_waitcnt vmcnt(31)
	ds_write_b32 v24, v11
	s_waitcnt vmcnt(30)
	ds_write_b32 v28, v13
	s_waitcnt vmcnt(29)
	ds_write_b32 v30, v58
	s_waitcnt vmcnt(28)
	ds_write_b32 v32, v59
	s_waitcnt vmcnt(27)
	ds_write_b32 v34, v60
	s_waitcnt vmcnt(26)
	ds_write_b32 v36, v61
	s_waitcnt vmcnt(25)
	ds_write_b32 v38, v62
	s_waitcnt vmcnt(24)
	ds_write_b32 v40, v63
	s_waitcnt vmcnt(23)
	ds_write_b32 v42, v64
	s_waitcnt vmcnt(22)
	ds_write_b32 v44, v65
	s_waitcnt vmcnt(21)
	ds_write_b32 v46, v66
	s_waitcnt vmcnt(20)
	ds_write_b32 v48, v67
	s_waitcnt vmcnt(19)
	ds_write_b32 v50, v6
	s_waitcnt vmcnt(18)
	ds_write_b32 v52, v68
	s_waitcnt vmcnt(17)
	ds_write_b32 v54, v69
	s_waitcnt vmcnt(16)
	ds_write_b32 v56, v70
	s_waitcnt vmcnt(15)
	ds_write_b32 v170, v157
	s_waitcnt vmcnt(14)
	ds_write_b32 v174, v159
	s_waitcnt vmcnt(13)
	ds_write_b32 v176, v204
	s_waitcnt vmcnt(12)
	ds_write_b32 v178, v205
	s_waitcnt vmcnt(11)
	ds_write_b32 v180, v206
	s_waitcnt vmcnt(10)
	ds_write_b32 v182, v207
	s_waitcnt vmcnt(9)
	ds_write_b32 v184, v208
	s_waitcnt vmcnt(8)
	ds_write_b32 v186, v209
	s_waitcnt vmcnt(7)
	ds_write_b32 v188, v210
	s_waitcnt vmcnt(6)
	ds_write_b32 v190, v211
	s_waitcnt vmcnt(5)
	ds_write_b32 v192, v212
	s_waitcnt vmcnt(4)
	ds_write_b32 v194, v213
	s_waitcnt vmcnt(3)
	ds_write_b32 v196, v152
	s_waitcnt vmcnt(2)
	ds_write_b32 v198, v214
	s_waitcnt vmcnt(1)
	ds_write_b32 v200, v215
	s_waitcnt vmcnt(0)
	ds_write_b32 v202, v216
	s_lshl_b64 s[8:9], s[8:9], 1
	s_waitcnt lgkmcnt(0)
	s_add_u32 s8, s35, s8
	ds_read2_b32 v[14:15], v23 offset0:33 offset1:41
	ds_read2_b32 v[24:25], v23 offset1:8
	ds_read2_b32 v[32:33], v23 offset0:66 offset1:74
	ds_read2_b32 v[34:35], v23 offset0:99 offset1:107
	ds_read2_b32 v[36:37], v23 offset0:132 offset1:140
	ds_read2_b32 v[38:39], v23 offset0:165 offset1:173
	ds_read2_b32 v[40:41], v23 offset0:198 offset1:206
	ds_read2_b32 v[42:43], v23 offset0:231 offset1:239
	s_addc_u32 s9, s44, s9
	s_lshl_b32 s10, s10, 1
	s_add_u32 s8, s8, s10
	s_addc_u32 s9, s9, 0
	v_mov_b32_e32 v13, v7
	v_or_b32_e32 v3, s6, v5
	v_lshl_add_u64 v[44:45], s[8:9], 0, v[12:13]
	v_lshlrev_b32_e32 v6, 11, v3
	s_waitcnt lgkmcnt(6)
	v_cvt_pk_bf16_f32 v28, v24, v14
	s_waitcnt lgkmcnt(4)
	v_cvt_pk_bf16_f32 v29, v32, v34
	s_waitcnt lgkmcnt(2)
	v_cvt_pk_bf16_f32 v30, v36, v38
	s_waitcnt lgkmcnt(0)
	v_cvt_pk_bf16_f32 v31, v40, v42
	v_lshl_add_u64 v[46:47], v[44:45], 0, v[6:7]
	global_store_dwordx4 v[46:47], v[28:31], off
	v_or_b32_e32 v3, s6, v9
	v_lshlrev_b32_e32 v6, 11, v3
	v_cvt_pk_bf16_f32 v28, v25, v15
	v_cvt_pk_bf16_f32 v29, v33, v35
	v_cvt_pk_bf16_f32 v30, v37, v39
	v_cvt_pk_bf16_f32 v31, v41, v43
	ds_read2_b32 v[24:25], v23 offset0:49 offset1:57
	ds_read2_b32 v[32:33], v23 offset0:16 offset1:24
	ds_read2_b32 v[34:35], v23 offset0:82 offset1:90
	ds_read2_b32 v[36:37], v23 offset0:115 offset1:123
	ds_read2_b32 v[38:39], v23 offset0:148 offset1:156
	ds_read2_b32 v[40:41], v23 offset0:181 offset1:189
	ds_read2_b32 v[42:43], v23 offset0:214 offset1:222
	ds_read2_b32 v[46:47], v23 offset0:247 offset1:255
	v_or_b32_e32 v3, s6, v17
	v_lshl_add_u64 v[14:15], v[44:45], 0, v[6:7]
	v_lshlrev_b32_e32 v6, 11, v3
	v_or_b32_e32 v3, s6, v18
	global_store_dwordx4 v[14:15], v[28:31], off
	v_lshl_add_u64 v[14:15], v[44:45], 0, v[6:7]
	v_lshlrev_b32_e32 v6, 11, v3
	s_waitcnt lgkmcnt(6)
	v_cvt_pk_bf16_f32 v28, v32, v24
	s_waitcnt lgkmcnt(4)
	v_cvt_pk_bf16_f32 v29, v34, v36
	s_waitcnt lgkmcnt(2)
	v_cvt_pk_bf16_f32 v30, v38, v40
	s_waitcnt lgkmcnt(0)
	v_cvt_pk_bf16_f32 v31, v42, v46
	global_store_dwordx4 v[14:15], v[28:31], off
	v_lshl_add_u64 v[14:15], v[44:45], 0, v[6:7]
	s_nop 0
	v_cvt_pk_bf16_f32 v28, v33, v25
	v_cvt_pk_bf16_f32 v29, v35, v37
	v_cvt_pk_bf16_f32 v30, v39, v41
	v_cvt_pk_bf16_f32 v31, v43, v47
	global_store_dwordx4 v[14:15], v[28:31], off
	s_waitcnt lgkmcnt(0)

.LBB0_55:
	s_lshl_b32 s51, s6, 1
	s_lshl_b32 s52, s9, 1
	v_or_b32_e32 v28, s52, v6
	s_add_i32 s53, s51, 4
	s_add_i32 s60, s52, 4
	s_add_i32 s61, s51, 8
	s_add_i32 s62, s52, 8
	s_add_i32 s63, s51, 12
	s_add_i32 s66, s52, 12
	s_add_i32 s67, s51, 16
	s_add_i32 s68, s52, 16
	s_add_i32 s69, s51, 20
	s_add_i32 s70, s52, 20
	s_add_i32 s71, s51, 24
	s_add_i32 s72, s52, 24
	s_add_i32 s73, s51, 28
	s_add_i32 s74, s52, 28
	v_or_b32_e32 v24, s51, v3
	v_ashrrev_i32_e32 v29, 31, v28
	v_or_b32_e32 v30, s53, v3
	v_or_b32_e32 v32, s60, v6
	v_or_b32_e32 v34, s61, v3
	v_or_b32_e32 v36, s62, v6
	v_or_b32_e32 v38, s63, v3
	v_or_b32_e32 v40, s66, v6
	v_or_b32_e32 v42, s67, v3
	v_or_b32_e32 v44, s68, v6
	v_or_b32_e32 v46, s69, v3
	v_or_b32_e32 v48, s70, v6
	v_or_b32_e32 v50, s71, v3
	v_or_b32_e32 v52, s72, v6
	v_or_b32_e32 v54, s73, v3
	v_or_b32_e32 v56, s74, v6
	v_ashrrev_i32_e32 v25, 31, v24
	v_lshlrev_b64 v[28:29], 13, v[28:29]
	v_ashrrev_i32_e32 v33, 31, v32
	v_ashrrev_i32_e32 v31, 31, v30
	v_ashrrev_i32_e32 v37, 31, v36
	v_ashrrev_i32_e32 v35, 31, v34
	v_ashrrev_i32_e32 v41, 31, v40
	v_ashrrev_i32_e32 v39, 31, v38
	v_ashrrev_i32_e32 v45, 31, v44
	v_ashrrev_i32_e32 v43, 31, v42
	v_ashrrev_i32_e32 v49, 31, v48
	v_ashrrev_i32_e32 v47, 31, v46
	v_ashrrev_i32_e32 v53, 31, v52
	v_ashrrev_i32_e32 v51, 31, v50
	v_ashrrev_i32_e32 v57, 31, v56
	v_ashrrev_i32_e32 v55, 31, v54
	v_lshlrev_b64 v[24:25], 13, v[24:25]
	v_lshl_add_u64 v[28:29], v[14:15], 0, v[28:29]
	v_lshlrev_b64 v[30:31], 13, v[30:31]
	v_lshlrev_b64 v[32:33], 13, v[32:33]
	v_lshlrev_b64 v[34:35], 13, v[34:35]
	v_lshlrev_b64 v[36:37], 13, v[36:37]
	v_lshlrev_b64 v[38:39], 13, v[38:39]
	v_lshlrev_b64 v[40:41], 13, v[40:41]
	v_lshlrev_b64 v[42:43], 13, v[42:43]
	v_lshlrev_b64 v[44:45], 13, v[44:45]
	v_lshlrev_b64 v[46:47], 13, v[46:47]
	v_lshlrev_b64 v[48:49], 13, v[48:49]
	v_lshlrev_b64 v[50:51], 13, v[50:51]
	v_lshlrev_b64 v[52:53], 13, v[52:53]
	v_lshlrev_b64 v[54:55], 13, v[54:55]
	v_lshlrev_b64 v[56:57], 13, v[56:57]
	v_lshl_add_u64 v[24:25], v[14:15], 0, v[24:25]
	v_lshl_add_u64 v[32:33], v[14:15], 0, v[32:33]
	v_lshl_add_u64 v[30:31], v[14:15], 0, v[30:31]
	v_lshl_add_u64 v[36:37], v[14:15], 0, v[36:37]
	v_lshl_add_u64 v[34:35], v[14:15], 0, v[34:35]
	v_lshl_add_u64 v[40:41], v[14:15], 0, v[40:41]
	v_lshl_add_u64 v[38:39], v[14:15], 0, v[38:39]
	v_lshl_add_u64 v[44:45], v[14:15], 0, v[44:45]
	v_lshl_add_u64 v[42:43], v[14:15], 0, v[42:43]
	v_lshl_add_u64 v[48:49], v[14:15], 0, v[48:49]
	v_lshl_add_u64 v[46:47], v[14:15], 0, v[46:47]
	v_lshl_add_u64 v[52:53], v[14:15], 0, v[52:53]
	v_lshl_add_u64 v[50:51], v[14:15], 0, v[50:51]
	v_lshl_add_u64 v[56:57], v[14:15], 0, v[56:57]
	v_lshl_add_u64 v[54:55], v[14:15], 0, v[54:55]
	global_load_dword v11, v[28:29], off
	global_load_dword v13, v[24:25], off
	global_load_dword v16, v[32:33], off
	global_load_dword v58, v[30:31], off
	global_load_dword v59, v[36:37], off
	global_load_dword v60, v[34:35], off
	global_load_dword v61, v[40:41], off
	global_load_dword v62, v[38:39], off
	global_load_dword v63, v[44:45], off
	global_load_dword v64, v[42:43], off
	global_load_dword v65, v[48:49], off
	global_load_dword v66, v[46:47], off
	global_load_dword v67, v[52:53], off
	global_load_dword v68, v[50:51], off
	global_load_dword v69, v[56:57], off
	global_load_dword v70, v[54:55], off
	v_or_b32_e32 v28, s51, v1
	v_or_b32_e32 v24, s52, v2
	s_add_i32 s9, s9, 16
	s_add_i32 s6, s6, 16
	s_add_i32 s13, s13, -16
	v_mad_u64_u32 v[24:25], s[64:65], v24, s16, v[8:9]
	v_mad_u64_u32 v[28:29], s[64:65], v28, s16, v[8:9]
	v_or_b32_e32 v25, s53, v1
	v_or_b32_e32 v29, s60, v2
	v_or_b32_e32 v36, s61, v1
	v_or_b32_e32 v34, s62, v2
	v_or_b32_e32 v40, s63, v1
	v_or_b32_e32 v38, s66, v2
	v_or_b32_e32 v44, s67, v1
	v_or_b32_e32 v42, s68, v2
	v_or_b32_e32 v48, s69, v1
	v_or_b32_e32 v46, s70, v2
	v_or_b32_e32 v52, s71, v1
	v_or_b32_e32 v50, s72, v2
	v_or_b32_e32 v56, s73, v1
	v_or_b32_e32 v54, s74, v2
	v_mad_u64_u32 v[30:31], s[52:53], v29, s16, v[8:9]
	v_mad_u64_u32 v[32:33], s[52:53], v25, s16, v[8:9]
	v_mad_u64_u32 v[34:35], s[52:53], v34, s16, v[8:9]
	v_mad_u64_u32 v[36:37], s[52:53], v36, s16, v[8:9]
	v_mad_u64_u32 v[38:39], s[52:53], v38, s16, v[8:9]
	v_mad_u64_u32 v[40:41], s[52:53], v40, s16, v[8:9]
	v_mad_u64_u32 v[42:43], s[52:53], v42, s16, v[8:9]
	v_mad_u64_u32 v[44:45], s[52:53], v44, s16, v[8:9]
	v_mad_u64_u32 v[46:47], s[52:53], v46, s16, v[8:9]
	v_mad_u64_u32 v[48:49], s[52:53], v48, s16, v[8:9]
	v_mad_u64_u32 v[50:51], s[52:53], v50, s16, v[8:9]
	v_mad_u64_u32 v[52:53], s[52:53], v52, s16, v[8:9]
	v_mad_u64_u32 v[54:55], s[52:53], v54, s16, v[8:9]
	v_mad_u64_u32 v[56:57], s[52:53], v56, s16, v[8:9]
	v_mov_b32_e32 v147, v1
	v_mov_b32_e32 v148, v2
	v_mov_b32_e32 v149, v3
	v_mov_b32_e32 v152, v6
	v_mov_b32_e32 v154, v8
	v_mov_b32_e32 v155, v9
	v_mov_b32_e32 v160, v14
	v_mov_b32_e32 v161, v15
	s_lshl_b32 s51, s6, 1
	s_lshl_b32 s52, s9, 1
	v_or_b32_e32 v174, s52, v152
	s_add_i32 s53, s51, 4
	s_add_i32 s60, s52, 4
	s_add_i32 s61, s51, 8
	s_add_i32 s62, s52, 8
	s_add_i32 s63, s51, 12
	s_add_i32 s66, s52, 12
	s_add_i32 s67, s51, 16
	s_add_i32 s68, s52, 16
	s_add_i32 s69, s51, 20
	s_add_i32 s70, s52, 20
	s_add_i32 s71, s51, 24
	s_add_i32 s72, s52, 24
	s_add_i32 s73, s51, 28
	s_add_i32 s74, s52, 28
	v_or_b32_e32 v170, s51, v149
	v_ashrrev_i32_e32 v175, 31, v174
	v_or_b32_e32 v176, s53, v149
	v_or_b32_e32 v178, s60, v152
	v_or_b32_e32 v180, s61, v149
	v_or_b32_e32 v182, s62, v152
	v_or_b32_e32 v184, s63, v149
	v_or_b32_e32 v186, s66, v152
	v_or_b32_e32 v188, s67, v149
	v_or_b32_e32 v190, s68, v152
	v_or_b32_e32 v192, s69, v149
	v_or_b32_e32 v194, s70, v152
	v_or_b32_e32 v196, s71, v149
	v_or_b32_e32 v198, s72, v152
	v_or_b32_e32 v200, s73, v149
	v_or_b32_e32 v202, s74, v152
	v_ashrrev_i32_e32 v171, 31, v170
	v_lshlrev_b64 v[174:175], 13, v[174:175]
	v_ashrrev_i32_e32 v179, 31, v178
	v_ashrrev_i32_e32 v177, 31, v176
	v_ashrrev_i32_e32 v183, 31, v182
	v_ashrrev_i32_e32 v181, 31, v180
	v_ashrrev_i32_e32 v187, 31, v186
	v_ashrrev_i32_e32 v185, 31, v184
	v_ashrrev_i32_e32 v191, 31, v190
	v_ashrrev_i32_e32 v189, 31, v188
	v_ashrrev_i32_e32 v195, 31, v194
	v_ashrrev_i32_e32 v193, 31, v192
	v_ashrrev_i32_e32 v199, 31, v198
	v_ashrrev_i32_e32 v197, 31, v196
	v_ashrrev_i32_e32 v203, 31, v202
	v_ashrrev_i32_e32 v201, 31, v200
	v_lshlrev_b64 v[170:171], 13, v[170:171]
	v_lshl_add_u64 v[174:175], v[160:161], 0, v[174:175]
	v_lshlrev_b64 v[176:177], 13, v[176:177]
	v_lshlrev_b64 v[178:179], 13, v[178:179]
	v_lshlrev_b64 v[180:181], 13, v[180:181]
	v_lshlrev_b64 v[182:183], 13, v[182:183]
	v_lshlrev_b64 v[184:185], 13, v[184:185]
	v_lshlrev_b64 v[186:187], 13, v[186:187]
	v_lshlrev_b64 v[188:189], 13, v[188:189]
	v_lshlrev_b64 v[190:191], 13, v[190:191]
	v_lshlrev_b64 v[192:193], 13, v[192:193]
	v_lshlrev_b64 v[194:195], 13, v[194:195]
	v_lshlrev_b64 v[196:197], 13, v[196:197]
	v_lshlrev_b64 v[198:199], 13, v[198:199]
	v_lshlrev_b64 v[200:201], 13, v[200:201]
	v_lshlrev_b64 v[202:203], 13, v[202:203]
	v_lshl_add_u64 v[170:171], v[160:161], 0, v[170:171]
	v_lshl_add_u64 v[178:179], v[160:161], 0, v[178:179]
	v_lshl_add_u64 v[176:177], v[160:161], 0, v[176:177]
	v_lshl_add_u64 v[182:183], v[160:161], 0, v[182:183]
	v_lshl_add_u64 v[180:181], v[160:161], 0, v[180:181]
	v_lshl_add_u64 v[186:187], v[160:161], 0, v[186:187]
	v_lshl_add_u64 v[184:185], v[160:161], 0, v[184:185]
	v_lshl_add_u64 v[190:191], v[160:161], 0, v[190:191]
	v_lshl_add_u64 v[188:189], v[160:161], 0, v[188:189]
	v_lshl_add_u64 v[194:195], v[160:161], 0, v[194:195]
	v_lshl_add_u64 v[192:193], v[160:161], 0, v[192:193]
	v_lshl_add_u64 v[198:199], v[160:161], 0, v[198:199]
	v_lshl_add_u64 v[196:197], v[160:161], 0, v[196:197]
	v_lshl_add_u64 v[202:203], v[160:161], 0, v[202:203]
	v_lshl_add_u64 v[200:201], v[160:161], 0, v[200:201]
	global_load_dword v157, v[174:175], off
	global_load_dword v159, v[170:171], off
	global_load_dword v162, v[178:179], off
	global_load_dword v204, v[176:177], off
	global_load_dword v205, v[182:183], off
	global_load_dword v206, v[180:181], off
	global_load_dword v207, v[186:187], off
	global_load_dword v208, v[184:185], off
	global_load_dword v209, v[190:191], off
	global_load_dword v210, v[188:189], off
	global_load_dword v211, v[194:195], off
	global_load_dword v212, v[192:193], off
	global_load_dword v213, v[198:199], off
	global_load_dword v214, v[196:197], off
	global_load_dword v215, v[202:203], off
	global_load_dword v216, v[200:201], off
	v_or_b32_e32 v174, s51, v147
	v_or_b32_e32 v170, s52, v148
	s_add_i32 s9, s9, 16
	s_add_i32 s6, s6, 16
	s_add_i32 s13, s13, -16
	v_mad_u64_u32 v[170:171], s[64:65], v170, s16, v[154:155]
	v_mad_u64_u32 v[174:175], s[64:65], v174, s16, v[154:155]
	v_or_b32_e32 v171, s53, v147
	v_or_b32_e32 v175, s60, v148
	v_or_b32_e32 v182, s61, v147
	v_or_b32_e32 v180, s62, v148
	v_or_b32_e32 v186, s63, v147
	v_or_b32_e32 v184, s66, v148
	v_or_b32_e32 v190, s67, v147
	v_or_b32_e32 v188, s68, v148
	v_or_b32_e32 v194, s69, v147
	v_or_b32_e32 v192, s70, v148
	v_or_b32_e32 v198, s71, v147
	v_or_b32_e32 v196, s72, v148
	v_or_b32_e32 v202, s73, v147
	v_or_b32_e32 v200, s74, v148
	v_mad_u64_u32 v[176:177], s[52:53], v175, s16, v[154:155]
	v_mad_u64_u32 v[178:179], s[52:53], v171, s16, v[154:155]
	v_mad_u64_u32 v[180:181], s[52:53], v180, s16, v[154:155]
	v_mad_u64_u32 v[182:183], s[52:53], v182, s16, v[154:155]
	v_mad_u64_u32 v[184:185], s[52:53], v184, s16, v[154:155]
	v_mad_u64_u32 v[186:187], s[52:53], v186, s16, v[154:155]
	v_mad_u64_u32 v[188:189], s[52:53], v188, s16, v[154:155]
	v_mad_u64_u32 v[190:191], s[52:53], v190, s16, v[154:155]
	v_mad_u64_u32 v[192:193], s[52:53], v192, s16, v[154:155]
	v_mad_u64_u32 v[194:195], s[52:53], v194, s16, v[154:155]
	v_mad_u64_u32 v[196:197], s[52:53], v196, s16, v[154:155]
	v_mad_u64_u32 v[198:199], s[52:53], v198, s16, v[154:155]
	v_mad_u64_u32 v[200:201], s[52:53], v200, s16, v[154:155]
	v_mad_u64_u32 v[202:203], s[52:53], v202, s16, v[154:155]
	s_waitcnt vmcnt(31)
	ds_write_b32 v24, v11
	s_waitcnt vmcnt(30)
	ds_write_b32 v28, v13
	s_waitcnt vmcnt(29)
	ds_write_b32 v30, v16
	s_waitcnt vmcnt(28)
	ds_write_b32 v32, v58
	s_waitcnt vmcnt(27)
	ds_write_b32 v34, v59
	s_waitcnt vmcnt(26)
	ds_write_b32 v36, v60
	s_waitcnt vmcnt(25)
	ds_write_b32 v38, v61
	s_waitcnt vmcnt(24)
	ds_write_b32 v40, v62
	s_waitcnt vmcnt(23)
	ds_write_b32 v42, v63
	s_waitcnt vmcnt(22)
	ds_write_b32 v44, v64
	s_waitcnt vmcnt(21)
	ds_write_b32 v46, v65
	s_waitcnt vmcnt(20)
	ds_write_b32 v48, v66
	s_waitcnt vmcnt(19)
	ds_write_b32 v50, v67
	s_waitcnt vmcnt(18)
	ds_write_b32 v52, v68
	s_waitcnt vmcnt(17)
	ds_write_b32 v54, v69
	s_waitcnt vmcnt(16)
	ds_write_b32 v56, v70
	s_waitcnt vmcnt(15)
	ds_write_b32 v170, v157
	s_waitcnt vmcnt(14)
	ds_write_b32 v174, v159
	s_waitcnt vmcnt(13)
	ds_write_b32 v176, v162
	s_waitcnt vmcnt(12)
	ds_write_b32 v178, v204
	s_waitcnt vmcnt(11)
	ds_write_b32 v180, v205
	s_waitcnt vmcnt(10)
	ds_write_b32 v182, v206
	s_waitcnt vmcnt(9)
	ds_write_b32 v184, v207
	s_waitcnt vmcnt(8)
	ds_write_b32 v186, v208
	s_waitcnt vmcnt(7)
	ds_write_b32 v188, v209
	s_waitcnt vmcnt(6)
	ds_write_b32 v190, v210
	s_waitcnt vmcnt(5)
	ds_write_b32 v192, v211
	s_waitcnt vmcnt(4)
	ds_write_b32 v194, v212
	s_waitcnt vmcnt(3)
	ds_write_b32 v196, v213
	s_waitcnt vmcnt(2)
	ds_write_b32 v198, v214
	s_waitcnt vmcnt(1)
	ds_write_b32 v200, v215
	s_waitcnt vmcnt(0)
	ds_write_b32 v202, v216
	s_lshl_b64 s[10:11], s[10:11], 1
	s_add_u32 s6, s45, s10
	s_waitcnt lgkmcnt(0)
	s_addc_u32 s9, s46, s11
	s_ashr_i32 s13, s12, 31
	ds_read2_b32 v[14:15], v23 offset0:33 offset1:41
	ds_read2_b32 v[24:25], v23 offset1:8
	ds_read2_b32 v[32:33], v23 offset0:66 offset1:74
	ds_read2_b32 v[34:35], v23 offset0:99 offset1:107
	ds_read2_b32 v[36:37], v23 offset0:132 offset1:140
	ds_read2_b32 v[38:39], v23 offset0:165 offset1:173
	ds_read2_b32 v[40:41], v23 offset0:198 offset1:206
	ds_read2_b32 v[42:43], v23 offset0:231 offset1:239
	s_lshl_b64 s[10:11], s[12:13], 1
	s_add_u32 s10, s6, s10
	v_or_b32_e32 v46, s8, v5
	s_addc_u32 s11, s9, s11
	v_mov_b32_e32 v13, v7
	v_ashrrev_i32_e32 v47, 31, v46
	v_lshl_add_u64 v[44:45], s[10:11], 0, v[12:13]
	v_lshlrev_b64 v[46:47], 11, v[46:47]
	s_waitcnt lgkmcnt(6)
	v_cvt_pk_bf16_f32 v28, v24, v14
	s_waitcnt lgkmcnt(4)
	v_cvt_pk_bf16_f32 v29, v32, v34
	s_waitcnt lgkmcnt(2)
	v_cvt_pk_bf16_f32 v30, v36, v38
	s_waitcnt lgkmcnt(0)
	v_cvt_pk_bf16_f32 v31, v40, v42
	v_lshl_add_u64 v[46:47], v[44:45], 0, v[46:47]
	v_or_b32_e32 v14, s8, v9
	global_store_dwordx4 v[46:47], v[28:31], off
	s_nop 1
	v_cvt_pk_bf16_f32 v28, v25, v15
	v_ashrrev_i32_e32 v15, 31, v14
	v_cvt_pk_bf16_f32 v29, v33, v35
	v_cvt_pk_bf16_f32 v30, v37, v39
	v_cvt_pk_bf16_f32 v31, v41, v43
	v_lshlrev_b64 v[14:15], 11, v[14:15]
	ds_read2_b32 v[24:25], v23 offset0:49 offset1:57
	ds_read2_b32 v[32:33], v23 offset0:16 offset1:24
	ds_read2_b32 v[34:35], v23 offset0:82 offset1:90
	ds_read2_b32 v[36:37], v23 offset0:115 offset1:123
	ds_read2_b32 v[38:39], v23 offset0:148 offset1:156
	ds_read2_b32 v[40:41], v23 offset0:181 offset1:189
	ds_read2_b32 v[42:43], v23 offset0:214 offset1:222
	ds_read2_b32 v[46:47], v23 offset0:247 offset1:255
	v_lshl_add_u64 v[14:15], v[44:45], 0, v[14:15]
	global_store_dwordx4 v[14:15], v[28:31], off
	v_or_b32_e32 v14, s8, v17
	v_ashrrev_i32_e32 v15, 31, v14
	v_lshlrev_b64 v[14:15], 11, v[14:15]
	s_waitcnt lgkmcnt(6)
	v_cvt_pk_bf16_f32 v28, v32, v24
	s_waitcnt lgkmcnt(4)
	v_cvt_pk_bf16_f32 v29, v34, v36
	s_waitcnt lgkmcnt(2)
	v_cvt_pk_bf16_f32 v30, v38, v40
	s_waitcnt lgkmcnt(0)
	v_cvt_pk_bf16_f32 v31, v42, v46
	v_lshl_add_u64 v[14:15], v[44:45], 0, v[14:15]
	global_store_dwordx4 v[14:15], v[28:31], off
	v_or_b32_e32 v14, s8, v18
	v_ashrrev_i32_e32 v15, 31, v14
	v_lshlrev_b64 v[14:15], 11, v[14:15]
	v_cvt_pk_bf16_f32 v28, v33, v25
	v_cvt_pk_bf16_f32 v29, v35, v37
	v_cvt_pk_bf16_f32 v30, v39, v41
	v_cvt_pk_bf16_f32 v31, v43, v47
	v_lshl_add_u64 v[14:15], v[44:45], 0, v[14:15]
	global_store_dwordx4 v[14:15], v[28:31], off
	s_waitcnt lgkmcnt(0)
	s_branch .LBB0_18

.Lcv2_loop:
	v_ashrrev_i32_e32 v64, 6, v68
	v_ashrrev_i32_e32 v65, 31, v64
	v_lshlrev_b64 v[70:71], 12, v[64:65]
	v_lshl_add_u64 v[70:71], s[16:17], 0, v[70:71]
	v_lshl_add_u64 v[70:71], v[70:71], 0, v[66:67]
	v_lshl_add_u64 v[74:75], v[70:71], 0, s[14:15]
	global_load_dwordx4 v[0:3], v[70:71], off offset:2048
	global_load_dwordx4 v[4:7], v[70:71], off offset:3072
	global_load_dwordx4 v[8:11], v[70:71], off offset:-2048
	global_load_dwordx4 v[12:15], v[70:71], off offset:-1024
	global_load_dwordx4 v[16:19], v[74:75], off offset:2048
	global_load_dwordx4 v[20:23], v[74:75], off offset:3072
	global_load_dwordx4 v[24:27], v[70:71], off offset:1024
	v_add_u32_e32 v69, s18, v68
	v_ashrrev_i32_e32 v190, 6, v69
	v_ashrrev_i32_e32 v191, 31, v190
	v_lshlrev_b64 v[184:185], 12, v[190:191]
	v_lshl_add_u64 v[184:185], s[16:17], 0, v[184:185]
	v_lshl_add_u64 v[184:185], v[184:185], 0, v[66:67]
	v_lshl_add_u64 v[188:189], v[184:185], 0, s[14:15]
	global_load_dwordx4 v[156:159], v[184:185], off offset:2048
	global_load_dwordx4 v[160:163], v[184:185], off offset:3072
	global_load_dwordx4 v[164:167], v[184:185], off offset:-2048
	global_load_dwordx4 v[168:171], v[184:185], off offset:-1024
	global_load_dwordx4 v[172:175], v[188:189], off offset:2048
	global_load_dwordx4 v[176:179], v[188:189], off offset:3072
	global_load_dwordx4 v[180:183], v[184:185], off offset:1024
	v_add_u32_e32 v187, s18, v69
	v_ashrrev_i32_e32 v194, 6, v187
	v_ashrrev_i32_e32 v195, 31, v194
	v_lshlrev_b64 v[196:197], 12, v[194:195]
	v_lshl_add_u64 v[196:197], s[16:17], 0, v[196:197]
	v_lshl_add_u64 v[196:197], v[196:197], 0, v[66:67]
	v_lshl_add_u64 v[198:199], v[196:197], 0, s[14:15]
	global_load_dwordx4 v[202:205], v[196:197], off offset:2048
	global_load_dwordx4 v[206:209], v[196:197], off offset:3072
	global_load_dwordx4 v[210:213], v[196:197], off offset:-2048
	global_load_dwordx4 v[214:217], v[196:197], off offset:-1024
	global_load_dwordx4 v[218:221], v[198:199], off offset:2048
	global_load_dwordx4 v[222:225], v[198:199], off offset:3072
	global_load_dwordx4 v[230:233], v[196:197], off offset:1024
	v_lshlrev_b64 v[72:73], 11, v[64:65]
	v_lshl_add_u64 v[72:73], s[32:33], 0, v[72:73]
	v_lshl_add_u64 v[72:73], v[72:73], 0, v[66:67]
	v_cmp_gt_i32_e32 vcc, 0x2000, v64
	s_nop 1
	v_cndmask_b32_e32 v76, v145, v144, vcc
	v_and_b32_e32 v147, v76, v64
	v_cmp_ne_u32_e64 s[10:11], 0, v147
	v_cmp_ne_u32_e64 s[12:13], v147, v76
	s_waitcnt vmcnt(19)
	v_lshlrev_b32_e32 v28, 16, v0
	v_and_b32_e32 v29, 0xffff0000, v0
	v_lshlrev_b32_e32 v30, 16, v4
	v_and_b32_e32 v31, 0xffff0000, v4
	v_pk_mul_f32 v[104:105], v[28:29], v[30:31]
	v_lshlrev_b32_e32 v28, 16, v1
	v_and_b32_e32 v29, 0xffff0000, v1
	v_lshlrev_b32_e32 v30, 16, v5
	v_and_b32_e32 v31, 0xffff0000, v5
	v_pk_mul_f32 v[106:107], v[28:29], v[30:31]
	v_lshlrev_b32_e32 v28, 16, v2
	v_and_b32_e32 v29, 0xffff0000, v2
	v_lshlrev_b32_e32 v30, 16, v6
	v_and_b32_e32 v31, 0xffff0000, v6
	v_pk_mul_f32 v[108:109], v[28:29], v[30:31]
	v_lshlrev_b32_e32 v28, 16, v3
	v_and_b32_e32 v29, 0xffff0000, v3
	v_lshlrev_b32_e32 v30, 16, v7
	v_and_b32_e32 v31, 0xffff0000, v7
	v_pk_mul_f32 v[110:111], v[28:29], v[30:31]
	s_waitcnt vmcnt(17)
	v_lshlrev_b32_e32 v28, 16, v8
	v_and_b32_e32 v29, 0xffff0000, v8
	v_lshlrev_b32_e32 v30, 16, v12
	v_and_b32_e32 v31, 0xffff0000, v12
	v_pk_mul_f32 v[96:97], v[28:29], v[30:31]
	v_lshlrev_b32_e32 v28, 16, v9
	v_and_b32_e32 v29, 0xffff0000, v9
	v_lshlrev_b32_e32 v30, 16, v13
	v_and_b32_e32 v31, 0xffff0000, v13
	v_pk_mul_f32 v[98:99], v[28:29], v[30:31]
	v_lshlrev_b32_e32 v28, 16, v10
	v_and_b32_e32 v29, 0xffff0000, v10
	v_lshlrev_b32_e32 v30, 16, v14
	v_and_b32_e32 v31, 0xffff0000, v14
	v_pk_mul_f32 v[100:101], v[28:29], v[30:31]
	v_lshlrev_b32_e32 v28, 16, v11
	v_and_b32_e32 v29, 0xffff0000, v11
	v_lshlrev_b32_e32 v30, 16, v15
	v_and_b32_e32 v31, 0xffff0000, v15
	v_pk_mul_f32 v[102:103], v[28:29], v[30:31]
	v_cndmask_b32_e64 v96, 0, v96, s[10:11]
	v_cndmask_b32_e64 v97, 0, v97, s[10:11]
	v_cndmask_b32_e64 v98, 0, v98, s[10:11]
	v_cndmask_b32_e64 v99, 0, v99, s[10:11]
	v_cndmask_b32_e64 v100, 0, v100, s[10:11]
	v_cndmask_b32_e64 v101, 0, v101, s[10:11]
	v_cndmask_b32_e64 v102, 0, v102, s[10:11]
	v_cndmask_b32_e64 v103, 0, v103, s[10:11]
	s_waitcnt vmcnt(15)
	v_lshlrev_b32_e32 v28, 16, v16
	v_and_b32_e32 v29, 0xffff0000, v16
	v_lshlrev_b32_e32 v30, 16, v20
	v_and_b32_e32 v31, 0xffff0000, v20
	v_pk_mul_f32 v[112:113], v[28:29], v[30:31]
	v_lshlrev_b32_e32 v28, 16, v17
	v_and_b32_e32 v29, 0xffff0000, v17
	v_lshlrev_b32_e32 v30, 16, v21
	v_and_b32_e32 v31, 0xffff0000, v21
	v_pk_mul_f32 v[114:115], v[28:29], v[30:31]
	v_lshlrev_b32_e32 v28, 16, v18
	v_and_b32_e32 v29, 0xffff0000, v18
	v_lshlrev_b32_e32 v30, 16, v22
	v_and_b32_e32 v31, 0xffff0000, v22
	v_pk_mul_f32 v[116:117], v[28:29], v[30:31]
	v_lshlrev_b32_e32 v28, 16, v19
	v_and_b32_e32 v29, 0xffff0000, v19
	v_lshlrev_b32_e32 v30, 16, v23
	v_and_b32_e32 v31, 0xffff0000, v23
	v_pk_mul_f32 v[118:119], v[28:29], v[30:31]
	v_cndmask_b32_e64 v112, 0, v112, s[12:13]
	v_cndmask_b32_e64 v113, 0, v113, s[12:13]
	v_cndmask_b32_e64 v114, 0, v114, s[12:13]
	v_cndmask_b32_e64 v115, 0, v115, s[12:13]
	v_cndmask_b32_e64 v116, 0, v116, s[12:13]
	v_cndmask_b32_e64 v117, 0, v117, s[12:13]
	v_cndmask_b32_e64 v118, 0, v118, s[12:13]
	v_cndmask_b32_e64 v119, 0, v119, s[12:13]
	s_waitcnt vmcnt(14)
	v_lshlrev_b32_e32 v120, 16, v24
	v_and_b32_e32 v121, 0xffff0000, v24
	v_lshlrev_b32_e32 v122, 16, v25
	v_and_b32_e32 v123, 0xffff0000, v25
	v_lshlrev_b32_e32 v124, 16, v26
	v_and_b32_e32 v125, 0xffff0000, v26
	v_lshlrev_b32_e32 v126, 16, v27
	v_and_b32_e32 v127, 0xffff0000, v27
	v_pk_mul_f32 v[148:149], v[104:105], v[40:41]
	v_pk_mul_f32 v[150:151], v[106:107], v[42:43]
	v_pk_mul_f32 v[152:153], v[108:109], v[44:45]
	v_pk_mul_f32 v[154:155], v[110:111], v[46:47]
	v_pk_fma_f32 v[148:149], v[96:97], v[32:33], v[148:149]
	v_pk_fma_f32 v[150:151], v[98:99], v[34:35], v[150:151]
	v_pk_fma_f32 v[152:153], v[100:101], v[36:37], v[152:153]
	v_pk_fma_f32 v[154:155], v[102:103], v[38:39], v[154:155]
	v_pk_fma_f32 v[148:149], v[112:113], v[48:49], v[148:149]
	v_pk_fma_f32 v[150:151], v[114:115], v[50:51], v[150:151]
	v_pk_fma_f32 v[152:153], v[116:117], v[52:53], v[152:153]
	v_pk_fma_f32 v[154:155], v[118:119], v[54:55], v[154:155]
	v_pk_add_f32 v[148:149], v[56:57], v[148:149]
	v_pk_add_f32 v[150:151], v[58:59], v[150:151]
	v_pk_add_f32 v[152:153], v[60:61], v[152:153]
	v_pk_add_f32 v[154:155], v[62:63], v[154:155]
	v_pk_mul_f32 v[148:149], v[148:149], v[120:121]
	v_pk_mul_f32 v[150:151], v[150:151], v[122:123]
	v_pk_mul_f32 v[152:153], v[152:153], v[124:125]
	v_pk_mul_f32 v[154:155], v[154:155], v[126:127]
	v_cvt_pk_bf16_f32 v28, v148, v149
	v_cvt_pk_bf16_f32 v29, v150, v151
	v_cvt_pk_bf16_f32 v30, v152, v153
	v_cvt_pk_bf16_f32 v31, v154, v155
	s_nop 0
	global_store_dwordx4 v[72:73], v[28:31], off
	v_lshlrev_b64 v[192:193], 11, v[190:191]
	v_lshl_add_u64 v[192:193], s[32:33], 0, v[192:193]
	v_lshl_add_u64 v[192:193], v[192:193], 0, v[66:67]
	v_cmp_gt_i32_e32 vcc, 0x2000, v190
	s_nop 1
	v_cndmask_b32_e32 v76, v145, v144, vcc
	v_and_b32_e32 v147, v76, v190
	v_cmp_ne_u32_e64 s[10:11], 0, v147
	v_cmp_ne_u32_e64 s[12:13], v147, v76
	v_cmp_gt_i32_e64 s[30:31], s19, v69
	s_waitcnt vmcnt(13)
	v_lshlrev_b32_e32 v28, 16, v156
	v_and_b32_e32 v29, 0xffff0000, v156
	v_lshlrev_b32_e32 v30, 16, v160
	v_and_b32_e32 v31, 0xffff0000, v160
	v_pk_mul_f32 v[104:105], v[28:29], v[30:31]
	v_lshlrev_b32_e32 v28, 16, v157
	v_and_b32_e32 v29, 0xffff0000, v157
	v_lshlrev_b32_e32 v30, 16, v161
	v_and_b32_e32 v31, 0xffff0000, v161
	v_pk_mul_f32 v[106:107], v[28:29], v[30:31]
	v_lshlrev_b32_e32 v28, 16, v158
	v_and_b32_e32 v29, 0xffff0000, v158
	v_lshlrev_b32_e32 v30, 16, v162
	v_and_b32_e32 v31, 0xffff0000, v162
	v_pk_mul_f32 v[108:109], v[28:29], v[30:31]
	v_lshlrev_b32_e32 v28, 16, v159
	v_and_b32_e32 v29, 0xffff0000, v159
	v_lshlrev_b32_e32 v30, 16, v163
	v_and_b32_e32 v31, 0xffff0000, v163
	v_pk_mul_f32 v[110:111], v[28:29], v[30:31]
	s_waitcnt vmcnt(11)
	v_lshlrev_b32_e32 v28, 16, v164
	v_and_b32_e32 v29, 0xffff0000, v164
	v_lshlrev_b32_e32 v30, 16, v168
	v_and_b32_e32 v31, 0xffff0000, v168
	v_pk_mul_f32 v[96:97], v[28:29], v[30:31]
	v_lshlrev_b32_e32 v28, 16, v165
	v_and_b32_e32 v29, 0xffff0000, v165
	v_lshlrev_b32_e32 v30, 16, v169
	v_and_b32_e32 v31, 0xffff0000, v169
	v_pk_mul_f32 v[98:99], v[28:29], v[30:31]
	v_lshlrev_b32_e32 v28, 16, v166
	v_and_b32_e32 v29, 0xffff0000, v166
	v_lshlrev_b32_e32 v30, 16, v170
	v_and_b32_e32 v31, 0xffff0000, v170
	v_pk_mul_f32 v[100:101], v[28:29], v[30:31]
	v_lshlrev_b32_e32 v28, 16, v167
	v_and_b32_e32 v29, 0xffff0000, v167
	v_lshlrev_b32_e32 v30, 16, v171
	v_and_b32_e32 v31, 0xffff0000, v171
	v_pk_mul_f32 v[102:103], v[28:29], v[30:31]
	v_cndmask_b32_e64 v96, 0, v96, s[10:11]
	v_cndmask_b32_e64 v97, 0, v97, s[10:11]
	v_cndmask_b32_e64 v98, 0, v98, s[10:11]
	v_cndmask_b32_e64 v99, 0, v99, s[10:11]
	v_cndmask_b32_e64 v100, 0, v100, s[10:11]
	v_cndmask_b32_e64 v101, 0, v101, s[10:11]
	v_cndmask_b32_e64 v102, 0, v102, s[10:11]
	v_cndmask_b32_e64 v103, 0, v103, s[10:11]
	s_waitcnt vmcnt(9)
	v_lshlrev_b32_e32 v28, 16, v172
	v_and_b32_e32 v29, 0xffff0000, v172
	v_lshlrev_b32_e32 v30, 16, v176
	v_and_b32_e32 v31, 0xffff0000, v176
	v_pk_mul_f32 v[112:113], v[28:29], v[30:31]
	v_lshlrev_b32_e32 v28, 16, v173
	v_and_b32_e32 v29, 0xffff0000, v173
	v_lshlrev_b32_e32 v30, 16, v177
	v_and_b32_e32 v31, 0xffff0000, v177
	v_pk_mul_f32 v[114:115], v[28:29], v[30:31]
	v_lshlrev_b32_e32 v28, 16, v174
	v_and_b32_e32 v29, 0xffff0000, v174
	v_lshlrev_b32_e32 v30, 16, v178
	v_and_b32_e32 v31, 0xffff0000, v178
	v_pk_mul_f32 v[116:117], v[28:29], v[30:31]
	v_lshlrev_b32_e32 v28, 16, v175
	v_and_b32_e32 v29, 0xffff0000, v175
	v_lshlrev_b32_e32 v30, 16, v179
	v_and_b32_e32 v31, 0xffff0000, v179
	v_pk_mul_f32 v[118:119], v[28:29], v[30:31]
	v_cndmask_b32_e64 v112, 0, v112, s[12:13]
	v_cndmask_b32_e64 v113, 0, v113, s[12:13]
	v_cndmask_b32_e64 v114, 0, v114, s[12:13]
	v_cndmask_b32_e64 v115, 0, v115, s[12:13]
	v_cndmask_b32_e64 v116, 0, v116, s[12:13]
	v_cndmask_b32_e64 v117, 0, v117, s[12:13]
	v_cndmask_b32_e64 v118, 0, v118, s[12:13]
	v_cndmask_b32_e64 v119, 0, v119, s[12:13]
	s_waitcnt vmcnt(8)
	v_lshlrev_b32_e32 v120, 16, v180
	v_and_b32_e32 v121, 0xffff0000, v180
	v_lshlrev_b32_e32 v122, 16, v181
	v_and_b32_e32 v123, 0xffff0000, v181
	v_lshlrev_b32_e32 v124, 16, v182
	v_and_b32_e32 v125, 0xffff0000, v182
	v_lshlrev_b32_e32 v126, 16, v183
	v_and_b32_e32 v127, 0xffff0000, v183
	v_pk_mul_f32 v[148:149], v[104:105], v[40:41]
	v_pk_mul_f32 v[150:151], v[106:107], v[42:43]
	v_pk_mul_f32 v[152:153], v[108:109], v[44:45]
	v_pk_mul_f32 v[154:155], v[110:111], v[46:47]
	v_pk_fma_f32 v[148:149], v[96:97], v[32:33], v[148:149]
	v_pk_fma_f32 v[150:151], v[98:99], v[34:35], v[150:151]
	v_pk_fma_f32 v[152:153], v[100:101], v[36:37], v[152:153]
	v_pk_fma_f32 v[154:155], v[102:103], v[38:39], v[154:155]
	v_pk_fma_f32 v[148:149], v[112:113], v[48:49], v[148:149]
	v_pk_fma_f32 v[150:151], v[114:115], v[50:51], v[150:151]
	v_pk_fma_f32 v[152:153], v[116:117], v[52:53], v[152:153]
	v_pk_fma_f32 v[154:155], v[118:119], v[54:55], v[154:155]
	v_pk_add_f32 v[148:149], v[56:57], v[148:149]
	v_pk_add_f32 v[150:151], v[58:59], v[150:151]
	v_pk_add_f32 v[152:153], v[60:61], v[152:153]
	v_pk_add_f32 v[154:155], v[62:63], v[154:155]
	v_pk_mul_f32 v[148:149], v[148:149], v[120:121]
	v_pk_mul_f32 v[150:151], v[150:151], v[122:123]
	v_pk_mul_f32 v[152:153], v[152:153], v[124:125]
	v_pk_mul_f32 v[154:155], v[154:155], v[126:127]
	v_cvt_pk_bf16_f32 v28, v148, v149
	v_cvt_pk_bf16_f32 v29, v150, v151
	v_cvt_pk_bf16_f32 v30, v152, v153
	v_cvt_pk_bf16_f32 v31, v154, v155
	s_nop 0
	s_and_saveexec_b64 s[8:9], s[30:31]
	global_store_dwordx4 v[192:193], v[28:31], off
	s_or_b64 exec, exec, s[8:9]
	v_lshlrev_b64 v[192:193], 11, v[194:195]
	v_lshl_add_u64 v[192:193], s[32:33], 0, v[192:193]
	v_lshl_add_u64 v[192:193], v[192:193], 0, v[66:67]
	v_cmp_gt_i32_e32 vcc, 0x2000, v194
	s_nop 1
	v_cndmask_b32_e32 v76, v145, v144, vcc
	v_and_b32_e32 v147, v76, v194
	v_cmp_ne_u32_e64 s[10:11], 0, v147
	v_cmp_ne_u32_e64 s[12:13], v147, v76
	v_cmp_gt_i32_e64 s[30:31], s19, v187
	s_waitcnt vmcnt(7)
	v_lshlrev_b32_e32 v28, 16, v202
	v_and_b32_e32 v29, 0xffff0000, v202
	v_lshlrev_b32_e32 v30, 16, v206
	v_and_b32_e32 v31, 0xffff0000, v206
	v_pk_mul_f32 v[104:105], v[28:29], v[30:31]
	v_lshlrev_b32_e32 v28, 16, v203
	v_and_b32_e32 v29, 0xffff0000, v203
	v_lshlrev_b32_e32 v30, 16, v207
	v_and_b32_e32 v31, 0xffff0000, v207
	v_pk_mul_f32 v[106:107], v[28:29], v[30:31]
	v_lshlrev_b32_e32 v28, 16, v204
	v_and_b32_e32 v29, 0xffff0000, v204
	v_lshlrev_b32_e32 v30, 16, v208
	v_and_b32_e32 v31, 0xffff0000, v208
	v_pk_mul_f32 v[108:109], v[28:29], v[30:31]
	v_lshlrev_b32_e32 v28, 16, v205
	v_and_b32_e32 v29, 0xffff0000, v205
	v_lshlrev_b32_e32 v30, 16, v209
	v_and_b32_e32 v31, 0xffff0000, v209
	v_pk_mul_f32 v[110:111], v[28:29], v[30:31]
	s_waitcnt vmcnt(5)
	v_lshlrev_b32_e32 v28, 16, v210
	v_and_b32_e32 v29, 0xffff0000, v210
	v_lshlrev_b32_e32 v30, 16, v214
	v_and_b32_e32 v31, 0xffff0000, v214
	v_pk_mul_f32 v[96:97], v[28:29], v[30:31]
	v_lshlrev_b32_e32 v28, 16, v211
	v_and_b32_e32 v29, 0xffff0000, v211
	v_lshlrev_b32_e32 v30, 16, v215
	v_and_b32_e32 v31, 0xffff0000, v215
	v_pk_mul_f32 v[98:99], v[28:29], v[30:31]
	v_lshlrev_b32_e32 v28, 16, v212
	v_and_b32_e32 v29, 0xffff0000, v212
	v_lshlrev_b32_e32 v30, 16, v216
	v_and_b32_e32 v31, 0xffff0000, v216
	v_pk_mul_f32 v[100:101], v[28:29], v[30:31]
	v_lshlrev_b32_e32 v28, 16, v213
	v_and_b32_e32 v29, 0xffff0000, v213
	v_lshlrev_b32_e32 v30, 16, v217
	v_and_b32_e32 v31, 0xffff0000, v217
	v_pk_mul_f32 v[102:103], v[28:29], v[30:31]
	v_cndmask_b32_e64 v96, 0, v96, s[10:11]
	v_cndmask_b32_e64 v97, 0, v97, s[10:11]
	v_cndmask_b32_e64 v98, 0, v98, s[10:11]
	v_cndmask_b32_e64 v99, 0, v99, s[10:11]
	v_cndmask_b32_e64 v100, 0, v100, s[10:11]
	v_cndmask_b32_e64 v101, 0, v101, s[10:11]
	v_cndmask_b32_e64 v102, 0, v102, s[10:11]
	v_cndmask_b32_e64 v103, 0, v103, s[10:11]
	s_waitcnt vmcnt(3)
	v_lshlrev_b32_e32 v28, 16, v218
	v_and_b32_e32 v29, 0xffff0000, v218
	v_lshlrev_b32_e32 v30, 16, v222
	v_and_b32_e32 v31, 0xffff0000, v222
	v_pk_mul_f32 v[112:113], v[28:29], v[30:31]
	v_lshlrev_b32_e32 v28, 16, v219
	v_and_b32_e32 v29, 0xffff0000, v219
	v_lshlrev_b32_e32 v30, 16, v223
	v_and_b32_e32 v31, 0xffff0000, v223
	v_pk_mul_f32 v[114:115], v[28:29], v[30:31]
	v_lshlrev_b32_e32 v28, 16, v220
	v_and_b32_e32 v29, 0xffff0000, v220
	v_lshlrev_b32_e32 v30, 16, v224
	v_and_b32_e32 v31, 0xffff0000, v224
	v_pk_mul_f32 v[116:117], v[28:29], v[30:31]
	v_lshlrev_b32_e32 v28, 16, v221
	v_and_b32_e32 v29, 0xffff0000, v221
	v_lshlrev_b32_e32 v30, 16, v225
	v_and_b32_e32 v31, 0xffff0000, v225
	v_pk_mul_f32 v[118:119], v[28:29], v[30:31]
	v_cndmask_b32_e64 v112, 0, v112, s[12:13]
	v_cndmask_b32_e64 v113, 0, v113, s[12:13]
	v_cndmask_b32_e64 v114, 0, v114, s[12:13]
	v_cndmask_b32_e64 v115, 0, v115, s[12:13]
	v_cndmask_b32_e64 v116, 0, v116, s[12:13]
	v_cndmask_b32_e64 v117, 0, v117, s[12:13]
	v_cndmask_b32_e64 v118, 0, v118, s[12:13]
	v_cndmask_b32_e64 v119, 0, v119, s[12:13]
	s_waitcnt vmcnt(2)
	v_lshlrev_b32_e32 v120, 16, v230
	v_and_b32_e32 v121, 0xffff0000, v230
	v_lshlrev_b32_e32 v122, 16, v231
	v_and_b32_e32 v123, 0xffff0000, v231
	v_lshlrev_b32_e32 v124, 16, v232
	v_and_b32_e32 v125, 0xffff0000, v232
	v_lshlrev_b32_e32 v126, 16, v233
	v_and_b32_e32 v127, 0xffff0000, v233
	v_pk_mul_f32 v[148:149], v[104:105], v[40:41]
	v_pk_mul_f32 v[150:151], v[106:107], v[42:43]
	v_pk_mul_f32 v[152:153], v[108:109], v[44:45]
	v_pk_mul_f32 v[154:155], v[110:111], v[46:47]
	v_pk_fma_f32 v[148:149], v[96:97], v[32:33], v[148:149]
	v_pk_fma_f32 v[150:151], v[98:99], v[34:35], v[150:151]
	v_pk_fma_f32 v[152:153], v[100:101], v[36:37], v[152:153]
	v_pk_fma_f32 v[154:155], v[102:103], v[38:39], v[154:155]
	v_pk_fma_f32 v[148:149], v[112:113], v[48:49], v[148:149]
	v_pk_fma_f32 v[150:151], v[114:115], v[50:51], v[150:151]
	v_pk_fma_f32 v[152:153], v[116:117], v[52:53], v[152:153]
	v_pk_fma_f32 v[154:155], v[118:119], v[54:55], v[154:155]
	v_pk_add_f32 v[148:149], v[56:57], v[148:149]
	v_pk_add_f32 v[150:151], v[58:59], v[150:151]
	v_pk_add_f32 v[152:153], v[60:61], v[152:153]
	v_pk_add_f32 v[154:155], v[62:63], v[154:155]
	v_pk_mul_f32 v[148:149], v[148:149], v[120:121]
	v_pk_mul_f32 v[150:151], v[150:151], v[122:123]
	v_pk_mul_f32 v[152:153], v[152:153], v[124:125]
	v_pk_mul_f32 v[154:155], v[154:155], v[126:127]
	v_cvt_pk_bf16_f32 v28, v148, v149
	v_cvt_pk_bf16_f32 v29, v150, v151
	v_cvt_pk_bf16_f32 v30, v152, v153
	v_cvt_pk_bf16_f32 v31, v154, v155
	s_nop 0
	s_and_saveexec_b64 s[8:9], s[30:31]
	global_store_dwordx4 v[192:193], v[28:31], off
	s_or_b64 exec, exec, s[8:9]
	v_add_u32_e32 v68, s18, v187
	v_cmp_gt_i32_e32 vcc, s19, v68
	s_nop 1
	s_and_b64 exec, exec, vcc
	s_cbranch_execnz .Lcv2_loop
